# k5 variant: in the merged GEMM K-loops the LDS-DMA issue blocks come before the ds_reads of each load segment (earlier DMA issue)
# baseline (speedup 1.0000x reference)
.LBB0_670:
	s_add_u32 s28, s34, 0xfff00080
	s_addc_u32 s29, s35, -1
	s_cmp_eq_u32 s94, 60
	s_cselect_b32 s39, s23, s29
	s_cselect_b32 s38, s22, s28
	s_cselect_b32 s37, s21, s93
	s_cselect_b32 s36, s20, s19
	v_lshl_add_u64 v[146:147], s[34:35], 0, v[142:143]
	s_add_i32 m0, s27, 0xc000
	s_nop 0
	global_load_lds_dwordx4 v[146:147], off
	v_lshl_add_u64 v[146:147], s[34:35], 0, v[140:141]
	s_add_i32 m0, s27, 0xe000
	s_nop 0
	global_load_lds_dwordx4 v[146:147], off
	ds_read_b128 v[154:157], v150
	ds_read_b128 v[158:161], v150 offset:1024
	ds_read_b128 v[162:165], v150 offset:2048
	ds_read_b128 v[166:169], v150 offset:3072
	ds_read_b128 v[202:205], v152
	ds_read_b128 v[206:209], v152 offset:1024
	ds_read_b128 v[210:213], v152 offset:2048
	ds_read_b128 v[214:217], v152 offset:3072
	ds_read_b128 v[170:173], v151
	ds_read_b128 v[174:177], v151 offset:1024
	ds_read_b128 v[178:181], v151 offset:2048
	ds_read_b128 v[182:185], v151 offset:3072
	ds_read_b128 v[186:189], v151 offset:4096
	ds_read_b128 v[190:193], v151 offset:5120
	ds_read_b128 v[194:197], v151 offset:6144
	ds_read_b128 v[198:201], v151 offset:7168
	s_waitcnt vmcnt(8)
	s_waitcnt lgkmcnt(0)
	s_barrier
	s_setprio 1
	v_mfma_f32_16x16x32_bf16 v[126:129], v[154:157], v[170:173], v[126:129]
	v_mfma_f32_16x16x32_bf16 v[122:125], v[162:165], v[170:173], v[122:125]
	v_mfma_f32_16x16x32_bf16 v[118:121], v[154:157], v[178:181], v[118:121]
	v_mfma_f32_16x16x32_bf16 v[110:113], v[162:165], v[178:181], v[110:113]
	v_mfma_f32_16x16x32_bf16 v[102:105], v[154:157], v[186:189], v[102:105]
	v_mfma_f32_16x16x32_bf16 v[94:97], v[162:165], v[186:189], v[94:97]
	v_mfma_f32_16x16x32_bf16 v[86:89], v[154:157], v[194:197], v[86:89]
	v_mfma_f32_16x16x32_bf16 v[78:81], v[162:165], v[194:197], v[78:81]
	v_mfma_f32_16x16x32_bf16 v[126:129], v[158:161], v[174:177], v[126:129]
	v_mfma_f32_16x16x32_bf16 v[122:125], v[166:169], v[174:177], v[122:125]
	v_mfma_f32_16x16x32_bf16 v[118:121], v[158:161], v[182:185], v[118:121]
	v_mfma_f32_16x16x32_bf16 v[110:113], v[166:169], v[182:185], v[110:113]
	v_mfma_f32_16x16x32_bf16 v[102:105], v[158:161], v[190:193], v[102:105]
	v_mfma_f32_16x16x32_bf16 v[94:97], v[166:169], v[190:193], v[94:97]
	v_mfma_f32_16x16x32_bf16 v[86:89], v[158:161], v[198:201], v[86:89]
	v_mfma_f32_16x16x32_bf16 v[78:81], v[166:169], v[198:201], v[78:81]
	v_mfma_f32_16x16x32_bf16 v[114:117], v[202:205], v[170:173], v[114:117]
	v_mfma_f32_16x16x32_bf16 v[106:109], v[210:213], v[170:173], v[106:109]
	v_mfma_f32_16x16x32_bf16 v[98:101], v[202:205], v[178:181], v[98:101]
	v_mfma_f32_16x16x32_bf16 v[90:93], v[210:213], v[178:181], v[90:93]
	v_mfma_f32_16x16x32_bf16 v[82:85], v[202:205], v[186:189], v[82:85]
	v_mfma_f32_16x16x32_bf16 v[74:77], v[210:213], v[186:189], v[74:77]
	v_mfma_f32_16x16x32_bf16 v[70:73], v[202:205], v[194:197], v[70:73]
	v_mfma_f32_16x16x32_bf16 v[66:69], v[210:213], v[194:197], v[66:69]
	v_mfma_f32_16x16x32_bf16 v[114:117], v[206:209], v[174:177], v[114:117]
	v_mfma_f32_16x16x32_bf16 v[106:109], v[214:217], v[174:177], v[106:109]
	v_mfma_f32_16x16x32_bf16 v[98:101], v[206:209], v[182:185], v[98:101]
	v_mfma_f32_16x16x32_bf16 v[90:93], v[214:217], v[182:185], v[90:93]
	v_mfma_f32_16x16x32_bf16 v[82:85], v[206:209], v[190:193], v[82:85]
	v_mfma_f32_16x16x32_bf16 v[74:77], v[214:217], v[190:193], v[74:77]
	v_mfma_f32_16x16x32_bf16 v[70:73], v[206:209], v[198:201], v[70:73]
	v_mfma_f32_16x16x32_bf16 v[66:69], v[214:217], v[198:201], v[66:69]
	s_setprio 0
	s_barrier
	s_add_i32 s28, s85, s74
	v_lshl_add_u64 v[146:147], s[36:37], 0, v[134:135]
	s_mov_b32 m0, s28
	s_nop 0
	global_load_lds_dwordx4 v[146:147], off
	v_lshl_add_u64 v[218:219], s[36:37], 0, v[130:131]
	s_add_i32 m0, s28, 0x2000
	s_nop 0
	global_load_lds_dwordx4 v[218:219], off
	s_mov_b32 m0, s27
	v_lshl_add_u64 v[220:221], s[38:39], 0, v[136:137]
	global_load_lds_dwordx4 v[220:221], off
	v_lshl_add_u64 v[222:223], s[38:39], 0, v[132:133]
	s_mov_b32 m0, s76
	s_nop 0
	global_load_lds_dwordx4 v[222:223], off
	s_add_u32 s28, s36, 0x100000
	s_addc_u32 s29, s37, 0
	s_add_i32 s95, s86, s74
	v_lshl_add_u64 v[226:227], s[28:29], 0, v[134:135]
	s_mov_b32 m0, s95
	s_nop 0
	global_load_lds_dwordx4 v[226:227], off
	v_lshl_add_u64 v[226:227], s[28:29], 0, v[130:131]
	s_add_i32 m0, s95, 0x2000
	s_nop 0
	global_load_lds_dwordx4 v[226:227], off
	ds_read_b128 v[170:173], v151 offset:16384
	ds_read_b128 v[174:177], v151 offset:17408
	ds_read_b128 v[178:181], v151 offset:18432
	ds_read_b128 v[182:185], v151 offset:19456
	ds_read_b128 v[186:189], v151 offset:20480
	ds_read_b128 v[190:193], v151 offset:21504
	ds_read_b128 v[194:197], v151 offset:22528
	ds_read_b128 v[198:201], v151 offset:23552
	s_waitcnt vmcnt(8)
	s_waitcnt lgkmcnt(0)
	s_barrier
	s_setprio 1
	v_mfma_f32_16x16x32_bf16 v[62:65], v[154:157], v[170:173], v[62:65]
	v_mfma_f32_16x16x32_bf16 v[58:61], v[162:165], v[170:173], v[58:61]
	v_mfma_f32_16x16x32_bf16 v[54:57], v[154:157], v[178:181], v[54:57]
	v_mfma_f32_16x16x32_bf16 v[46:49], v[162:165], v[178:181], v[46:49]
	v_mfma_f32_16x16x32_bf16 v[38:41], v[154:157], v[186:189], v[38:41]
	v_mfma_f32_16x16x32_bf16 v[30:33], v[162:165], v[186:189], v[30:33]
	v_mfma_f32_16x16x32_bf16 v[22:25], v[154:157], v[194:197], v[22:25]
	v_mfma_f32_16x16x32_bf16 v[14:17], v[162:165], v[194:197], v[14:17]
	v_mfma_f32_16x16x32_bf16 v[62:65], v[158:161], v[174:177], v[62:65]
	v_mfma_f32_16x16x32_bf16 v[58:61], v[166:169], v[174:177], v[58:61]
	v_mfma_f32_16x16x32_bf16 v[54:57], v[158:161], v[182:185], v[54:57]
	v_mfma_f32_16x16x32_bf16 v[46:49], v[166:169], v[182:185], v[46:49]
	v_mfma_f32_16x16x32_bf16 v[38:41], v[158:161], v[190:193], v[38:41]
	v_mfma_f32_16x16x32_bf16 v[30:33], v[166:169], v[190:193], v[30:33]
	v_mfma_f32_16x16x32_bf16 v[22:25], v[158:161], v[198:201], v[22:25]
	v_mfma_f32_16x16x32_bf16 v[14:17], v[166:169], v[198:201], v[14:17]
	v_mfma_f32_16x16x32_bf16 v[50:53], v[202:205], v[170:173], v[50:53]
	v_mfma_f32_16x16x32_bf16 v[42:45], v[210:213], v[170:173], v[42:45]
	v_mfma_f32_16x16x32_bf16 v[34:37], v[202:205], v[178:181], v[34:37]
	v_mfma_f32_16x16x32_bf16 v[26:29], v[210:213], v[178:181], v[26:29]
	v_mfma_f32_16x16x32_bf16 v[18:21], v[202:205], v[186:189], v[18:21]
	v_mfma_f32_16x16x32_bf16 v[10:13], v[210:213], v[186:189], v[10:13]
	v_mfma_f32_16x16x32_bf16 v[6:9], v[202:205], v[194:197], v[6:9]
	v_mfma_f32_16x16x32_bf16 v[2:5], v[210:213], v[194:197], v[2:5]
	v_mfma_f32_16x16x32_bf16 v[50:53], v[206:209], v[174:177], v[50:53]
	v_mfma_f32_16x16x32_bf16 v[42:45], v[214:217], v[174:177], v[42:45]
	v_mfma_f32_16x16x32_bf16 v[34:37], v[206:209], v[182:185], v[34:37]
	v_mfma_f32_16x16x32_bf16 v[26:29], v[214:217], v[182:185], v[26:29]
	v_mfma_f32_16x16x32_bf16 v[18:21], v[206:209], v[190:193], v[18:21]
	v_mfma_f32_16x16x32_bf16 v[10:13], v[214:217], v[190:193], v[10:13]
	v_mfma_f32_16x16x32_bf16 v[6:9], v[206:209], v[198:201], v[6:9]
	v_mfma_f32_16x16x32_bf16 v[2:5], v[214:217], v[198:201], v[2:5]
	s_setprio 0
	s_add_i32 s95, 0, 0x18000
	v_add_u32_e32 v153, s95, v148
	s_barrier
	s_add_u32 s28, s38, 0x100000
	s_addc_u32 s29, s39, 0
	s_mov_b32 m0, s77
	v_lshl_add_u64 v[226:227], s[28:29], 0, v[136:137]
	global_load_lds_dwordx4 v[226:227], off
	v_lshl_add_u64 v[226:227], s[28:29], 0, v[132:133]
	s_mov_b32 m0, s78
	s_nop 0
	global_load_lds_dwordx4 v[226:227], off
	ds_read_b128 v[154:157], v153
	ds_read_b128 v[158:161], v153 offset:1024
	ds_read_b128 v[162:165], v153 offset:2048
	ds_read_b128 v[166:169], v153 offset:3072
	ds_read_b128 v[202:205], v153 offset:16384
	ds_read_b128 v[206:209], v153 offset:17408
	ds_read_b128 v[210:213], v153 offset:18432
	ds_read_b128 v[214:217], v153 offset:19456
	ds_read_b128 v[170:173], v151 offset:32768
	ds_read_b128 v[174:177], v151 offset:33792
	ds_read_b128 v[178:181], v151 offset:34816
	ds_read_b128 v[182:185], v151 offset:35840
	ds_read_b128 v[186:189], v151 offset:36864
	ds_read_b128 v[190:193], v151 offset:37888
	ds_read_b128 v[194:197], v151 offset:38912
	ds_read_b128 v[198:201], v151 offset:39936
	s_waitcnt vmcnt(8)
	s_waitcnt lgkmcnt(0)
	s_barrier
	s_setprio 1
	v_mfma_f32_16x16x32_bf16 v[126:129], v[154:157], v[170:173], v[126:129]
	v_mfma_f32_16x16x32_bf16 v[122:125], v[162:165], v[170:173], v[122:125]
	v_mfma_f32_16x16x32_bf16 v[118:121], v[154:157], v[178:181], v[118:121]
	v_mfma_f32_16x16x32_bf16 v[110:113], v[162:165], v[178:181], v[110:113]
	v_mfma_f32_16x16x32_bf16 v[102:105], v[154:157], v[186:189], v[102:105]
	v_mfma_f32_16x16x32_bf16 v[94:97], v[162:165], v[186:189], v[94:97]
	v_mfma_f32_16x16x32_bf16 v[86:89], v[154:157], v[194:197], v[86:89]
	v_mfma_f32_16x16x32_bf16 v[78:81], v[162:165], v[194:197], v[78:81]
	v_mfma_f32_16x16x32_bf16 v[126:129], v[158:161], v[174:177], v[126:129]
	v_mfma_f32_16x16x32_bf16 v[122:125], v[166:169], v[174:177], v[122:125]
	v_mfma_f32_16x16x32_bf16 v[118:121], v[158:161], v[182:185], v[118:121]
	v_mfma_f32_16x16x32_bf16 v[110:113], v[166:169], v[182:185], v[110:113]
	v_mfma_f32_16x16x32_bf16 v[102:105], v[158:161], v[190:193], v[102:105]
	v_mfma_f32_16x16x32_bf16 v[94:97], v[166:169], v[190:193], v[94:97]
	v_mfma_f32_16x16x32_bf16 v[86:89], v[158:161], v[198:201], v[86:89]
	v_mfma_f32_16x16x32_bf16 v[78:81], v[166:169], v[198:201], v[78:81]
	v_mfma_f32_16x16x32_bf16 v[114:117], v[202:205], v[170:173], v[114:117]
	v_mfma_f32_16x16x32_bf16 v[106:109], v[210:213], v[170:173], v[106:109]
	v_mfma_f32_16x16x32_bf16 v[98:101], v[202:205], v[178:181], v[98:101]
	v_mfma_f32_16x16x32_bf16 v[90:93], v[210:213], v[178:181], v[90:93]
	v_mfma_f32_16x16x32_bf16 v[82:85], v[202:205], v[186:189], v[82:85]
	v_mfma_f32_16x16x32_bf16 v[74:77], v[210:213], v[186:189], v[74:77]
	v_mfma_f32_16x16x32_bf16 v[70:73], v[202:205], v[194:197], v[70:73]
	v_mfma_f32_16x16x32_bf16 v[66:69], v[210:213], v[194:197], v[66:69]
	v_mfma_f32_16x16x32_bf16 v[114:117], v[206:209], v[174:177], v[114:117]
	v_mfma_f32_16x16x32_bf16 v[106:109], v[214:217], v[174:177], v[106:109]
	v_mfma_f32_16x16x32_bf16 v[98:101], v[206:209], v[182:185], v[98:101]
	v_mfma_f32_16x16x32_bf16 v[90:93], v[214:217], v[182:185], v[90:93]
	v_mfma_f32_16x16x32_bf16 v[82:85], v[206:209], v[190:193], v[82:85]
	v_mfma_f32_16x16x32_bf16 v[74:77], v[214:217], v[190:193], v[74:77]
	v_mfma_f32_16x16x32_bf16 v[70:73], v[206:209], v[198:201], v[70:73]
	v_mfma_f32_16x16x32_bf16 v[66:69], v[214:217], v[198:201], v[66:69]
	s_setprio 0
	s_barrier
	s_add_i32 s38, 0, 0x1c000
	s_add_i32 s28, s95, s74
	v_lshl_add_u64 v[146:147], v[146:147], 0, s[0:1]
	s_mov_b32 m0, s28
	s_nop 0
	global_load_lds_dwordx4 v[146:147], off
	v_lshl_add_u64 v[146:147], v[218:219], 0, s[0:1]
	s_add_i32 m0, s28, 0x2000
	s_nop 0
	global_load_lds_dwordx4 v[146:147], off
	s_mov_b32 m0, s80
	v_lshl_add_u64 v[146:147], v[220:221], 0, s[0:1]
	global_load_lds_dwordx4 v[146:147], off
	v_lshl_add_u64 v[146:147], v[222:223], 0, s[0:1]
	s_mov_b32 m0, s81
	s_nop 0
	global_load_lds_dwordx4 v[146:147], off
	s_add_u32 s28, s36, 0x100080
	s_addc_u32 s29, s37, 0
	s_add_i32 s36, s38, s74
	v_lshl_add_u64 v[146:147], s[28:29], 0, v[134:135]
	s_mov_b32 m0, s36
	s_nop 0
	global_load_lds_dwordx4 v[146:147], off
	v_lshl_add_u64 v[146:147], s[28:29], 0, v[130:131]
	s_add_i32 m0, s36, 0x2000
	s_nop 0
	global_load_lds_dwordx4 v[146:147], off
	ds_read_b128 v[170:173], v151 offset:49152
	ds_read_b128 v[174:177], v151 offset:50176
	ds_read_b128 v[178:181], v151 offset:51200
	ds_read_b128 v[182:185], v151 offset:52224
	ds_read_b128 v[186:189], v151 offset:53248
	ds_read_b128 v[190:193], v151 offset:54272
	ds_read_b128 v[194:197], v151 offset:55296
	ds_read_b128 v[198:201], v151 offset:56320
	s_waitcnt vmcnt(8)
	s_waitcnt lgkmcnt(0)
	s_barrier
	s_setprio 1
	v_mfma_f32_16x16x32_bf16 v[62:65], v[154:157], v[170:173], v[62:65]
	v_mfma_f32_16x16x32_bf16 v[58:61], v[162:165], v[170:173], v[58:61]
	v_mfma_f32_16x16x32_bf16 v[54:57], v[154:157], v[178:181], v[54:57]
	v_mfma_f32_16x16x32_bf16 v[46:49], v[162:165], v[178:181], v[46:49]
	v_mfma_f32_16x16x32_bf16 v[38:41], v[154:157], v[186:189], v[38:41]
	v_mfma_f32_16x16x32_bf16 v[30:33], v[162:165], v[186:189], v[30:33]
	v_mfma_f32_16x16x32_bf16 v[22:25], v[154:157], v[194:197], v[22:25]
	v_mfma_f32_16x16x32_bf16 v[14:17], v[162:165], v[194:197], v[14:17]
	v_mfma_f32_16x16x32_bf16 v[62:65], v[158:161], v[174:177], v[62:65]
	v_mfma_f32_16x16x32_bf16 v[58:61], v[166:169], v[174:177], v[58:61]
	v_mfma_f32_16x16x32_bf16 v[54:57], v[158:161], v[182:185], v[54:57]
	v_mfma_f32_16x16x32_bf16 v[46:49], v[166:169], v[182:185], v[46:49]
	v_mfma_f32_16x16x32_bf16 v[38:41], v[158:161], v[190:193], v[38:41]
	v_mfma_f32_16x16x32_bf16 v[30:33], v[166:169], v[190:193], v[30:33]
	v_mfma_f32_16x16x32_bf16 v[22:25], v[158:161], v[198:201], v[22:25]
	v_mfma_f32_16x16x32_bf16 v[14:17], v[166:169], v[198:201], v[14:17]
	v_mfma_f32_16x16x32_bf16 v[50:53], v[202:205], v[170:173], v[50:53]
	v_mfma_f32_16x16x32_bf16 v[42:45], v[210:213], v[170:173], v[42:45]
	v_mfma_f32_16x16x32_bf16 v[34:37], v[202:205], v[178:181], v[34:37]
	v_mfma_f32_16x16x32_bf16 v[26:29], v[210:213], v[178:181], v[26:29]
	v_mfma_f32_16x16x32_bf16 v[18:21], v[202:205], v[186:189], v[18:21]
	v_mfma_f32_16x16x32_bf16 v[10:13], v[210:213], v[186:189], v[10:13]
	v_mfma_f32_16x16x32_bf16 v[6:9], v[202:205], v[194:197], v[6:9]
	v_mfma_f32_16x16x32_bf16 v[2:5], v[210:213], v[194:197], v[2:5]
	v_mfma_f32_16x16x32_bf16 v[50:53], v[206:209], v[174:177], v[50:53]
	v_mfma_f32_16x16x32_bf16 v[42:45], v[214:217], v[174:177], v[42:45]
	v_mfma_f32_16x16x32_bf16 v[34:37], v[206:209], v[182:185], v[34:37]
	v_mfma_f32_16x16x32_bf16 v[26:29], v[214:217], v[182:185], v[26:29]
	v_mfma_f32_16x16x32_bf16 v[18:21], v[206:209], v[190:193], v[18:21]
	v_mfma_f32_16x16x32_bf16 v[10:13], v[214:217], v[190:193], v[10:13]
	v_mfma_f32_16x16x32_bf16 v[6:9], v[206:209], v[198:201], v[6:9]
	v_mfma_f32_16x16x32_bf16 v[2:5], v[214:217], v[198:201], v[2:5]
	s_setprio 0
	s_add_i32 s94, s94, 2
	s_add_u32 s19, s19, 0x100
	s_addc_u32 s93, s93, 0
	s_add_u32 s34, s34, 0x100
	s_addc_u32 s35, s35, 0
	s_cmp_gt_u32 s94, 61
	s_barrier
	s_cbranch_scc0 .LBB0_670
	s_cmp_lt_i32 s92, 2
	s_cbranch_scc1 .LBB0_675
	s_cmp_eq_u32 s92, 2
	s_mov_b64 s[34:35], -1
	s_cbranch_scc0 .LBB0_674
	v_lshl_add_u32 v146, s26, 8, v1
	v_or_b32_e32 v156, 16, v146
	v_ashrrev_i32_e32 v147, 31, v146
	v_ashrrev_i32_e32 v157, 31, v156
	v_lshlrev_b64 v[154:155], 10, v[146:147]
	v_lshlrev_b64 v[156:157], 10, v[156:157]
	v_lshl_add_u64 v[154:155], v[138:139], 0, v[154:155]
	v_lshl_add_u64 v[156:157], v[138:139], 0, v[156:157]
	global_store_dwordx4 v[154:155], v[126:129], off
	global_store_dwordx4 v[154:155], v[122:125], off offset:16
	global_store_dwordx4 v[154:155], v[114:117], off offset:512
	global_store_dwordx4 v[154:155], v[106:109], off offset:528
	global_store_dwordx4 v[156:157], v[118:121], off
	global_store_dwordx4 v[156:157], v[110:113], off offset:16
	global_store_dwordx4 v[156:157], v[98:101], off offset:512
	global_store_dwordx4 v[156:157], v[90:93], off offset:528
	v_or_b32_e32 v156, 32, v146
	v_ashrrev_i32_e32 v157, 31, v156
	v_lshlrev_b64 v[156:157], 10, v[156:157]
	v_or_b32_e32 v146, 48, v146
	v_lshl_add_u64 v[156:157], v[138:139], 0, v[156:157]
	v_ashrrev_i32_e32 v147, 31, v146
	global_store_dwordx4 v[156:157], v[102:105], off
	global_store_dwordx4 v[156:157], v[94:97], off offset:16
	global_store_dwordx4 v[156:157], v[82:85], off offset:512
	global_store_dwordx4 v[156:157], v[74:77], off offset:528
	v_lshlrev_b64 v[146:147], 10, v[146:147]
	v_add_co_u32_e32 v156, vcc, s87, v154
	v_lshl_add_u64 v[146:147], v[138:139], 0, v[146:147]
	s_mov_b64 s[28:29], 0x20000
	v_addc_co_u32_e32 v157, vcc, 0, v155, vcc
	global_store_dwordx4 v[146:147], v[86:89], off
	global_store_dwordx4 v[146:147], v[78:81], off offset:16
	global_store_dwordx4 v[146:147], v[70:73], off offset:512
	global_store_dwordx4 v[146:147], v[66:69], off offset:528
	v_lshl_add_u64 v[146:147], v[154:155], 0, s[28:29]
	global_store_dwordx4 v[156:157], v[62:65], off
	global_store_dwordx4 v[146:147], v[58:61], off offset:16
	global_store_dwordx4 v[146:147], v[50:53], off offset:512
	global_store_dwordx4 v[146:147], v[42:45], off offset:528
	v_add_co_u32_e32 v156, vcc, s88, v154
	v_lshl_add_u64 v[146:147], v[154:155], 0, s[6:7]
	s_nop 0
	v_addc_co_u32_e32 v157, vcc, 0, v155, vcc
	global_store_dwordx4 v[156:157], v[54:57], off
	global_store_dwordx4 v[146:147], v[46:49], off offset:16
	global_store_dwordx4 v[146:147], v[34:37], off offset:512
	global_store_dwordx4 v[146:147], v[26:29], off offset:528
	v_add_co_u32_e32 v156, vcc, s89, v154
	v_lshl_add_u64 v[146:147], v[154:155], 0, s[12:13]
	s_nop 0
	v_addc_co_u32_e32 v157, vcc, 0, v155, vcc
	global_store_dwordx4 v[156:157], v[38:41], off
	global_store_dwordx4 v[146:147], v[30:33], off offset:16
	global_store_dwordx4 v[146:147], v[18:21], off offset:512
	global_store_dwordx4 v[146:147], v[10:13], off offset:528
	v_lshl_add_u64 v[146:147], v[154:155], 0, s[14:15]
	v_add_co_u32_e32 v154, vcc, 0x2c000, v154
	s_mov_b64 s[34:35], 0
	s_nop 0
	v_addc_co_u32_e32 v155, vcc, 0, v155, vcc
	global_store_dwordx4 v[154:155], v[22:25], off
	global_store_dwordx4 v[146:147], v[14:17], off offset:16
	global_store_dwordx4 v[146:147], v[6:9], off offset:512
	global_store_dwordx4 v[146:147], v[2:5], off offset:528

.LBB0_2485:
	s_add_u32 s28, s50, 0xfff00080
	s_addc_u32 s29, s51, -1
	s_cmp_eq_u32 s81, 60
	s_cselect_b32 s55, s45, s29
	s_cselect_b32 s54, s44, s28
	s_cselect_b32 s53, s47, s41
	s_cselect_b32 s52, s46, s39
	v_lshl_add_u64 v[144:145], s[50:51], 0, v[140:141]
	s_add_i32 m0, s49, 0xc000
	s_nop 0
	global_load_lds_dwordx4 v[144:145], off
	v_lshl_add_u64 v[144:145], s[50:51], 0, v[138:139]
	s_add_i32 m0, s49, 0xe000
	s_nop 0
	global_load_lds_dwordx4 v[144:145], off
	ds_read_b128 v[152:155], v148
	ds_read_b128 v[156:159], v148 offset:1024
	ds_read_b128 v[160:163], v148 offset:2048
	ds_read_b128 v[164:167], v148 offset:3072
	ds_read_b128 v[200:203], v150
	ds_read_b128 v[204:207], v150 offset:1024
	ds_read_b128 v[208:211], v150 offset:2048
	ds_read_b128 v[212:215], v150 offset:3072
	ds_read_b128 v[168:171], v149
	ds_read_b128 v[172:175], v149 offset:1024
	ds_read_b128 v[176:179], v149 offset:2048
	ds_read_b128 v[180:183], v149 offset:3072
	ds_read_b128 v[184:187], v149 offset:4096
	ds_read_b128 v[188:191], v149 offset:5120
	ds_read_b128 v[192:195], v149 offset:6144
	ds_read_b128 v[196:199], v149 offset:7168
	s_waitcnt vmcnt(8)
	s_waitcnt lgkmcnt(0)
	s_barrier
	s_setprio 1
	v_mfma_f32_16x16x32_bf16 v[126:129], v[152:155], v[168:171], v[126:129]
	v_mfma_f32_16x16x32_bf16 v[122:125], v[160:163], v[168:171], v[122:125]
	v_mfma_f32_16x16x32_bf16 v[114:117], v[152:155], v[176:179], v[114:117]
	v_mfma_f32_16x16x32_bf16 v[106:109], v[160:163], v[176:179], v[106:109]
	v_mfma_f32_16x16x32_bf16 v[98:101], v[152:155], v[184:187], v[98:101]
	v_mfma_f32_16x16x32_bf16 v[90:93], v[160:163], v[184:187], v[90:93]
	v_mfma_f32_16x16x32_bf16 v[82:85], v[152:155], v[192:195], v[82:85]
	v_mfma_f32_16x16x32_bf16 v[74:77], v[160:163], v[192:195], v[74:77]
	v_mfma_f32_16x16x32_bf16 v[126:129], v[156:159], v[172:175], v[126:129]
	v_mfma_f32_16x16x32_bf16 v[122:125], v[164:167], v[172:175], v[122:125]
	v_mfma_f32_16x16x32_bf16 v[114:117], v[156:159], v[180:183], v[114:117]
	v_mfma_f32_16x16x32_bf16 v[106:109], v[164:167], v[180:183], v[106:109]
	v_mfma_f32_16x16x32_bf16 v[98:101], v[156:159], v[188:191], v[98:101]
	v_mfma_f32_16x16x32_bf16 v[90:93], v[164:167], v[188:191], v[90:93]
	v_mfma_f32_16x16x32_bf16 v[82:85], v[156:159], v[196:199], v[82:85]
	v_mfma_f32_16x16x32_bf16 v[74:77], v[164:167], v[196:199], v[74:77]
	v_mfma_f32_16x16x32_bf16 v[118:121], v[200:203], v[168:171], v[118:121]
	v_mfma_f32_16x16x32_bf16 v[110:113], v[208:211], v[168:171], v[110:113]
	v_mfma_f32_16x16x32_bf16 v[102:105], v[200:203], v[176:179], v[102:105]
	v_mfma_f32_16x16x32_bf16 v[94:97], v[208:211], v[176:179], v[94:97]
	v_mfma_f32_16x16x32_bf16 v[86:89], v[200:203], v[184:187], v[86:89]
	v_mfma_f32_16x16x32_bf16 v[78:81], v[208:211], v[184:187], v[78:81]
	v_mfma_f32_16x16x32_bf16 v[70:73], v[200:203], v[192:195], v[70:73]
	v_mfma_f32_16x16x32_bf16 v[66:69], v[208:211], v[192:195], v[66:69]
	v_mfma_f32_16x16x32_bf16 v[118:121], v[204:207], v[172:175], v[118:121]
	v_mfma_f32_16x16x32_bf16 v[110:113], v[212:215], v[172:175], v[110:113]
	v_mfma_f32_16x16x32_bf16 v[102:105], v[204:207], v[180:183], v[102:105]
	v_mfma_f32_16x16x32_bf16 v[94:97], v[212:215], v[180:183], v[94:97]
	v_mfma_f32_16x16x32_bf16 v[86:89], v[204:207], v[188:191], v[86:89]
	v_mfma_f32_16x16x32_bf16 v[78:81], v[212:215], v[188:191], v[78:81]
	v_mfma_f32_16x16x32_bf16 v[70:73], v[204:207], v[196:199], v[70:73]
	v_mfma_f32_16x16x32_bf16 v[66:69], v[212:215], v[196:199], v[66:69]
	s_setprio 0
	s_barrier
	s_add_i32 s28, s74, s67
	v_lshl_add_u64 v[144:145], s[52:53], 0, v[134:135]
	s_mov_b32 m0, s28
	s_nop 0
	global_load_lds_dwordx4 v[144:145], off
	v_lshl_add_u64 v[216:217], s[52:53], 0, v[130:131]
	s_add_i32 m0, s28, 0x2000
	s_nop 0
	global_load_lds_dwordx4 v[216:217], off
	s_mov_b32 m0, s49
	v_lshl_add_u64 v[218:219], s[54:55], 0, v[136:137]
	global_load_lds_dwordx4 v[218:219], off
	v_lshl_add_u64 v[220:221], s[54:55], 0, v[132:133]
	s_mov_b32 m0, s68
	s_nop 0
	global_load_lds_dwordx4 v[220:221], off
	s_add_u32 s28, s52, 0x100000
	s_addc_u32 s29, s53, 0
	s_add_i32 s82, s75, s67
	v_lshl_add_u64 v[226:227], s[28:29], 0, v[134:135]
	s_mov_b32 m0, s82
	s_nop 0
	global_load_lds_dwordx4 v[226:227], off
	v_lshl_add_u64 v[226:227], s[28:29], 0, v[130:131]
	s_add_i32 m0, s82, 0x2000
	s_nop 0
	global_load_lds_dwordx4 v[226:227], off
	ds_read_b128 v[168:171], v149 offset:16384
	ds_read_b128 v[172:175], v149 offset:17408
	ds_read_b128 v[176:179], v149 offset:18432
	ds_read_b128 v[180:183], v149 offset:19456
	ds_read_b128 v[184:187], v149 offset:20480
	ds_read_b128 v[188:191], v149 offset:21504
	ds_read_b128 v[192:195], v149 offset:22528
	ds_read_b128 v[196:199], v149 offset:23552
	s_waitcnt vmcnt(8)
	s_waitcnt lgkmcnt(0)
	s_barrier
	s_setprio 1
	v_mfma_f32_16x16x32_bf16 v[62:65], v[152:155], v[168:171], v[62:65]
	v_mfma_f32_16x16x32_bf16 v[58:61], v[160:163], v[168:171], v[58:61]
	v_mfma_f32_16x16x32_bf16 v[54:57], v[152:155], v[176:179], v[54:57]
	v_mfma_f32_16x16x32_bf16 v[46:49], v[160:163], v[176:179], v[46:49]
	v_mfma_f32_16x16x32_bf16 v[38:41], v[152:155], v[184:187], v[38:41]
	v_mfma_f32_16x16x32_bf16 v[30:33], v[160:163], v[184:187], v[30:33]
	v_mfma_f32_16x16x32_bf16 v[22:25], v[152:155], v[192:195], v[22:25]
	v_mfma_f32_16x16x32_bf16 v[14:17], v[160:163], v[192:195], v[14:17]
	v_mfma_f32_16x16x32_bf16 v[62:65], v[156:159], v[172:175], v[62:65]
	v_mfma_f32_16x16x32_bf16 v[58:61], v[164:167], v[172:175], v[58:61]
	v_mfma_f32_16x16x32_bf16 v[54:57], v[156:159], v[180:183], v[54:57]
	v_mfma_f32_16x16x32_bf16 v[46:49], v[164:167], v[180:183], v[46:49]
	v_mfma_f32_16x16x32_bf16 v[38:41], v[156:159], v[188:191], v[38:41]
	v_mfma_f32_16x16x32_bf16 v[30:33], v[164:167], v[188:191], v[30:33]
	v_mfma_f32_16x16x32_bf16 v[22:25], v[156:159], v[196:199], v[22:25]
	v_mfma_f32_16x16x32_bf16 v[14:17], v[164:167], v[196:199], v[14:17]
	v_mfma_f32_16x16x32_bf16 v[50:53], v[200:203], v[168:171], v[50:53]
	v_mfma_f32_16x16x32_bf16 v[42:45], v[208:211], v[168:171], v[42:45]
	v_mfma_f32_16x16x32_bf16 v[34:37], v[200:203], v[176:179], v[34:37]
	v_mfma_f32_16x16x32_bf16 v[26:29], v[208:211], v[176:179], v[26:29]
	v_mfma_f32_16x16x32_bf16 v[18:21], v[200:203], v[184:187], v[18:21]
	v_mfma_f32_16x16x32_bf16 v[10:13], v[208:211], v[184:187], v[10:13]
	v_mfma_f32_16x16x32_bf16 v[6:9], v[200:203], v[192:195], v[6:9]
	v_mfma_f32_16x16x32_bf16 v[2:5], v[208:211], v[192:195], v[2:5]
	v_mfma_f32_16x16x32_bf16 v[50:53], v[204:207], v[172:175], v[50:53]
	v_mfma_f32_16x16x32_bf16 v[42:45], v[212:215], v[172:175], v[42:45]
	v_mfma_f32_16x16x32_bf16 v[34:37], v[204:207], v[180:183], v[34:37]
	v_mfma_f32_16x16x32_bf16 v[26:29], v[212:215], v[180:183], v[26:29]
	v_mfma_f32_16x16x32_bf16 v[18:21], v[204:207], v[188:191], v[18:21]
	v_mfma_f32_16x16x32_bf16 v[10:13], v[212:215], v[188:191], v[10:13]
	v_mfma_f32_16x16x32_bf16 v[6:9], v[204:207], v[196:199], v[6:9]
	v_mfma_f32_16x16x32_bf16 v[2:5], v[212:215], v[196:199], v[2:5]
	s_setprio 0
	s_add_i32 s82, 0, 0x18000
	v_add_u32_e32 v151, s82, v146
	s_barrier
	s_add_u32 s28, s54, 0x100000
	s_addc_u32 s29, s55, 0
	s_mov_b32 m0, s69
	v_lshl_add_u64 v[226:227], s[28:29], 0, v[136:137]
	global_load_lds_dwordx4 v[226:227], off
	v_lshl_add_u64 v[226:227], s[28:29], 0, v[132:133]
	s_mov_b32 m0, s70
	s_nop 0
	global_load_lds_dwordx4 v[226:227], off
	ds_read_b128 v[152:155], v151
	ds_read_b128 v[156:159], v151 offset:1024
	ds_read_b128 v[160:163], v151 offset:2048
	ds_read_b128 v[164:167], v151 offset:3072
	ds_read_b128 v[200:203], v151 offset:16384
	ds_read_b128 v[204:207], v151 offset:17408
	ds_read_b128 v[208:211], v151 offset:18432
	ds_read_b128 v[212:215], v151 offset:19456
	ds_read_b128 v[168:171], v149 offset:32768
	ds_read_b128 v[172:175], v149 offset:33792
	ds_read_b128 v[176:179], v149 offset:34816
	ds_read_b128 v[180:183], v149 offset:35840
	ds_read_b128 v[184:187], v149 offset:36864
	ds_read_b128 v[188:191], v149 offset:37888
	ds_read_b128 v[192:195], v149 offset:38912
	ds_read_b128 v[196:199], v149 offset:39936
	s_waitcnt vmcnt(8)
	s_waitcnt lgkmcnt(0)
	s_barrier
	s_setprio 1
	v_mfma_f32_16x16x32_bf16 v[126:129], v[152:155], v[168:171], v[126:129]
	v_mfma_f32_16x16x32_bf16 v[122:125], v[160:163], v[168:171], v[122:125]
	v_mfma_f32_16x16x32_bf16 v[114:117], v[152:155], v[176:179], v[114:117]
	v_mfma_f32_16x16x32_bf16 v[106:109], v[160:163], v[176:179], v[106:109]
	v_mfma_f32_16x16x32_bf16 v[98:101], v[152:155], v[184:187], v[98:101]
	v_mfma_f32_16x16x32_bf16 v[90:93], v[160:163], v[184:187], v[90:93]
	v_mfma_f32_16x16x32_bf16 v[82:85], v[152:155], v[192:195], v[82:85]
	v_mfma_f32_16x16x32_bf16 v[74:77], v[160:163], v[192:195], v[74:77]
	v_mfma_f32_16x16x32_bf16 v[126:129], v[156:159], v[172:175], v[126:129]
	v_mfma_f32_16x16x32_bf16 v[122:125], v[164:167], v[172:175], v[122:125]
	v_mfma_f32_16x16x32_bf16 v[114:117], v[156:159], v[180:183], v[114:117]
	v_mfma_f32_16x16x32_bf16 v[106:109], v[164:167], v[180:183], v[106:109]
	v_mfma_f32_16x16x32_bf16 v[98:101], v[156:159], v[188:191], v[98:101]
	v_mfma_f32_16x16x32_bf16 v[90:93], v[164:167], v[188:191], v[90:93]
	v_mfma_f32_16x16x32_bf16 v[82:85], v[156:159], v[196:199], v[82:85]
	v_mfma_f32_16x16x32_bf16 v[74:77], v[164:167], v[196:199], v[74:77]
	v_mfma_f32_16x16x32_bf16 v[118:121], v[200:203], v[168:171], v[118:121]
	v_mfma_f32_16x16x32_bf16 v[110:113], v[208:211], v[168:171], v[110:113]
	v_mfma_f32_16x16x32_bf16 v[102:105], v[200:203], v[176:179], v[102:105]
	v_mfma_f32_16x16x32_bf16 v[94:97], v[208:211], v[176:179], v[94:97]
	v_mfma_f32_16x16x32_bf16 v[86:89], v[200:203], v[184:187], v[86:89]
	v_mfma_f32_16x16x32_bf16 v[78:81], v[208:211], v[184:187], v[78:81]
	v_mfma_f32_16x16x32_bf16 v[70:73], v[200:203], v[192:195], v[70:73]
	v_mfma_f32_16x16x32_bf16 v[66:69], v[208:211], v[192:195], v[66:69]
	v_mfma_f32_16x16x32_bf16 v[118:121], v[204:207], v[172:175], v[118:121]
	v_mfma_f32_16x16x32_bf16 v[110:113], v[212:215], v[172:175], v[110:113]
	v_mfma_f32_16x16x32_bf16 v[102:105], v[204:207], v[180:183], v[102:105]
	v_mfma_f32_16x16x32_bf16 v[94:97], v[212:215], v[180:183], v[94:97]
	v_mfma_f32_16x16x32_bf16 v[86:89], v[204:207], v[188:191], v[86:89]
	v_mfma_f32_16x16x32_bf16 v[78:81], v[212:215], v[188:191], v[78:81]
	v_mfma_f32_16x16x32_bf16 v[70:73], v[204:207], v[196:199], v[70:73]
	v_mfma_f32_16x16x32_bf16 v[66:69], v[212:215], v[196:199], v[66:69]
	s_setprio 0
	s_barrier
	s_add_i32 s54, 0, 0x1c000
	s_add_i32 s28, s82, s67
	v_lshl_add_u64 v[144:145], v[144:145], 0, s[22:23]
	s_mov_b32 m0, s28
	s_nop 0
	global_load_lds_dwordx4 v[144:145], off
	v_lshl_add_u64 v[144:145], v[216:217], 0, s[22:23]
	s_add_i32 m0, s28, 0x2000
	s_nop 0
	global_load_lds_dwordx4 v[144:145], off
	s_mov_b32 m0, s72
	v_lshl_add_u64 v[144:145], v[218:219], 0, s[22:23]
	global_load_lds_dwordx4 v[144:145], off
	v_lshl_add_u64 v[144:145], v[220:221], 0, s[22:23]
	s_mov_b32 m0, s73
	s_nop 0
	global_load_lds_dwordx4 v[144:145], off
	s_add_u32 s28, s52, 0x100080
	s_addc_u32 s29, s53, 0
	s_add_i32 s52, s54, s67
	v_lshl_add_u64 v[144:145], s[28:29], 0, v[134:135]
	s_mov_b32 m0, s52
	s_nop 0
	global_load_lds_dwordx4 v[144:145], off
	v_lshl_add_u64 v[144:145], s[28:29], 0, v[130:131]
	s_add_i32 m0, s52, 0x2000
	s_nop 0
	global_load_lds_dwordx4 v[144:145], off
	ds_read_b128 v[168:171], v149 offset:49152
	ds_read_b128 v[172:175], v149 offset:50176
	ds_read_b128 v[176:179], v149 offset:51200
	ds_read_b128 v[180:183], v149 offset:52224
	ds_read_b128 v[184:187], v149 offset:53248
	ds_read_b128 v[188:191], v149 offset:54272
	ds_read_b128 v[192:195], v149 offset:55296
	ds_read_b128 v[196:199], v149 offset:56320
	s_waitcnt vmcnt(8)
	s_waitcnt lgkmcnt(0)
	s_barrier
	s_setprio 1
	v_mfma_f32_16x16x32_bf16 v[62:65], v[152:155], v[168:171], v[62:65]
	v_mfma_f32_16x16x32_bf16 v[58:61], v[160:163], v[168:171], v[58:61]
	v_mfma_f32_16x16x32_bf16 v[54:57], v[152:155], v[176:179], v[54:57]
	v_mfma_f32_16x16x32_bf16 v[46:49], v[160:163], v[176:179], v[46:49]
	v_mfma_f32_16x16x32_bf16 v[38:41], v[152:155], v[184:187], v[38:41]
	v_mfma_f32_16x16x32_bf16 v[30:33], v[160:163], v[184:187], v[30:33]
	v_mfma_f32_16x16x32_bf16 v[22:25], v[152:155], v[192:195], v[22:25]
	v_mfma_f32_16x16x32_bf16 v[14:17], v[160:163], v[192:195], v[14:17]
	v_mfma_f32_16x16x32_bf16 v[62:65], v[156:159], v[172:175], v[62:65]
	v_mfma_f32_16x16x32_bf16 v[58:61], v[164:167], v[172:175], v[58:61]
	v_mfma_f32_16x16x32_bf16 v[54:57], v[156:159], v[180:183], v[54:57]
	v_mfma_f32_16x16x32_bf16 v[46:49], v[164:167], v[180:183], v[46:49]
	v_mfma_f32_16x16x32_bf16 v[38:41], v[156:159], v[188:191], v[38:41]
	v_mfma_f32_16x16x32_bf16 v[30:33], v[164:167], v[188:191], v[30:33]
	v_mfma_f32_16x16x32_bf16 v[22:25], v[156:159], v[196:199], v[22:25]
	v_mfma_f32_16x16x32_bf16 v[14:17], v[164:167], v[196:199], v[14:17]
	v_mfma_f32_16x16x32_bf16 v[50:53], v[200:203], v[168:171], v[50:53]
	v_mfma_f32_16x16x32_bf16 v[42:45], v[208:211], v[168:171], v[42:45]
	v_mfma_f32_16x16x32_bf16 v[34:37], v[200:203], v[176:179], v[34:37]
	v_mfma_f32_16x16x32_bf16 v[26:29], v[208:211], v[176:179], v[26:29]
	v_mfma_f32_16x16x32_bf16 v[18:21], v[200:203], v[184:187], v[18:21]
	v_mfma_f32_16x16x32_bf16 v[10:13], v[208:211], v[184:187], v[10:13]
	v_mfma_f32_16x16x32_bf16 v[6:9], v[200:203], v[192:195], v[6:9]
	v_mfma_f32_16x16x32_bf16 v[2:5], v[208:211], v[192:195], v[2:5]
	v_mfma_f32_16x16x32_bf16 v[50:53], v[204:207], v[172:175], v[50:53]
	v_mfma_f32_16x16x32_bf16 v[42:45], v[212:215], v[172:175], v[42:45]
	v_mfma_f32_16x16x32_bf16 v[34:37], v[204:207], v[180:183], v[34:37]
	v_mfma_f32_16x16x32_bf16 v[26:29], v[212:215], v[180:183], v[26:29]
	v_mfma_f32_16x16x32_bf16 v[18:21], v[204:207], v[188:191], v[18:21]
	v_mfma_f32_16x16x32_bf16 v[10:13], v[212:215], v[188:191], v[10:13]
	v_mfma_f32_16x16x32_bf16 v[6:9], v[204:207], v[196:199], v[6:9]
	v_mfma_f32_16x16x32_bf16 v[2:5], v[212:215], v[196:199], v[2:5]
	s_setprio 0
	s_add_i32 s81, s81, 2
	s_add_u32 s39, s39, 0x100
	s_addc_u32 s41, s41, 0
	s_add_u32 s50, s50, 0x100
	s_addc_u32 s51, s51, 0
	s_cmp_gt_u32 s81, 61
	s_barrier
	s_cbranch_scc0 .LBB0_2485
	v_lshl_add_u32 v152, s48, 8, v1
	v_lshl_or_b32 v144, s80, 8, v147
	v_ashrrev_i32_e32 v153, 31, v152
	v_ashrrev_i32_e32 v145, 31, v144
	v_lshlrev_b64 v[154:155], 13, v[152:153]
	v_lshl_add_u64 v[154:155], s[18:19], 0, v[154:155]
	v_lshlrev_b64 v[156:157], 1, v[144:145]
	v_lshl_add_u64 v[144:145], v[154:155], 0, v[156:157]
	v_cvt_pk_bf16_f32 v126, v126, v127
	v_cvt_pk_bf16_f32 v127, v128, v129
	v_cvt_pk_bf16_f32 v128, v122, v123
	v_cvt_pk_bf16_f32 v129, v124, v125
	global_store_dwordx4 v[144:145], v[126:129], off
	v_cvt_pk_bf16_f32 v118, v118, v119
	v_cvt_pk_bf16_f32 v119, v120, v121
	v_cvt_pk_bf16_f32 v120, v110, v111
	v_or_b32_e32 v110, 16, v152
	v_ashrrev_i32_e32 v111, 31, v110
	v_lshlrev_b64 v[110:111], 13, v[110:111]
	v_lshl_add_u64 v[110:111], s[18:19], 0, v[110:111]
	v_cvt_pk_bf16_f32 v121, v112, v113
	global_store_dwordx4 v[144:145], v[118:121], off offset:256
	s_mov_b32 s48, s40
	s_mov_b32 s80, s38
	v_lshl_add_u64 v[118:119], v[110:111], 0, v[156:157]
	v_cvt_pk_bf16_f32 v110, v114, v115
	v_cvt_pk_bf16_f32 v111, v116, v117
	v_cvt_pk_bf16_f32 v112, v106, v107
	v_cvt_pk_bf16_f32 v113, v108, v109
	global_store_dwordx4 v[118:119], v[110:113], off
	v_cvt_pk_bf16_f32 v102, v102, v103
	v_cvt_pk_bf16_f32 v103, v104, v105
	v_cvt_pk_bf16_f32 v104, v94, v95
	v_or_b32_e32 v94, 32, v152
	v_ashrrev_i32_e32 v95, 31, v94
	v_lshlrev_b64 v[94:95], 13, v[94:95]
	v_lshl_add_u64 v[94:95], s[18:19], 0, v[94:95]
	v_cvt_pk_bf16_f32 v105, v96, v97
	global_store_dwordx4 v[118:119], v[102:105], off offset:256
	s_mov_b64 s[52:53], s[46:47]
	s_mov_b64 s[50:51], s[44:45]
	v_lshl_add_u64 v[102:103], v[94:95], 0, v[156:157]
	v_cvt_pk_bf16_f32 v94, v98, v99
	v_cvt_pk_bf16_f32 v95, v100, v101
	v_cvt_pk_bf16_f32 v96, v90, v91
	v_cvt_pk_bf16_f32 v97, v92, v93
	global_store_dwordx4 v[102:103], v[94:97], off
	v_cvt_pk_bf16_f32 v86, v86, v87
	v_cvt_pk_bf16_f32 v87, v88, v89
	v_cvt_pk_bf16_f32 v88, v78, v79
	v_or_b32_e32 v78, 48, v152
	v_ashrrev_i32_e32 v79, 31, v78
	v_lshlrev_b64 v[78:79], 13, v[78:79]
	v_lshl_add_u64 v[78:79], s[18:19], 0, v[78:79]
	v_cvt_pk_bf16_f32 v89, v80, v81
	global_store_dwordx4 v[102:103], v[86:89], off offset:256
	s_nop 1
	v_lshl_add_u64 v[86:87], v[78:79], 0, v[156:157]
	v_cvt_pk_bf16_f32 v78, v82, v83
	v_cvt_pk_bf16_f32 v79, v84, v85
	v_cvt_pk_bf16_f32 v80, v74, v75
	v_cvt_pk_bf16_f32 v81, v76, v77
	global_store_dwordx4 v[86:87], v[78:81], off
	v_cvt_pk_bf16_f32 v70, v70, v71
	v_cvt_pk_bf16_f32 v71, v72, v73
	v_cvt_pk_bf16_f32 v72, v66, v67
	v_cvt_pk_bf16_f32 v73, v68, v69
	global_store_dwordx4 v[86:87], v[70:73], off offset:256
	v_cvt_pk_bf16_f32 v62, v62, v63
	v_cvt_pk_bf16_f32 v63, v64, v65
	v_cvt_pk_bf16_f32 v64, v58, v59
	v_add_co_u32_e32 v58, vcc, s76, v144
	v_lshl_add_u64 v[66:67], v[144:145], 0, s[20:21]
	s_nop 0
	v_addc_co_u32_e32 v59, vcc, 0, v145, vcc
	v_cvt_pk_bf16_f32 v65, v60, v61
	global_store_dwordx4 v[58:59], v[62:65], off
	v_cvt_pk_bf16_f32 v50, v50, v51
	v_cvt_pk_bf16_f32 v51, v52, v53
	v_cvt_pk_bf16_f32 v52, v42, v43
	v_cvt_pk_bf16_f32 v53, v44, v45
	global_store_dwordx4 v[66:67], v[50:53], off offset:256
	v_cvt_pk_bf16_f32 v42, v54, v55
	v_cvt_pk_bf16_f32 v43, v56, v57
	v_cvt_pk_bf16_f32 v44, v46, v47
	v_add_co_u32_e32 v46, vcc, s77, v144
	s_nop 0
	v_lshl_add_u64 v[50:51], v[144:145], 0, s[26:27]
	v_addc_co_u32_e32 v47, vcc, 0, v145, vcc
	v_cvt_pk_bf16_f32 v45, v48, v49
	global_store_dwordx4 v[46:47], v[42:45], off
	v_cvt_pk_bf16_f32 v34, v34, v35
	v_cvt_pk_bf16_f32 v35, v36, v37
	v_cvt_pk_bf16_f32 v36, v26, v27
	v_cvt_pk_bf16_f32 v37, v28, v29
	global_store_dwordx4 v[50:51], v[34:37], off offset:256
	v_cvt_pk_bf16_f32 v26, v38, v39
	v_cvt_pk_bf16_f32 v27, v40, v41
	v_cvt_pk_bf16_f32 v28, v30, v31
	v_add_co_u32_e32 v30, vcc, s78, v144
	s_nop 0
	v_lshl_add_u64 v[34:35], v[144:145], 0, s[34:35]
	v_addc_co_u32_e32 v31, vcc, 0, v145, vcc
	v_cvt_pk_bf16_f32 v29, v32, v33
	global_store_dwordx4 v[30:31], v[26:29], off
	v_cvt_pk_bf16_f32 v18, v18, v19
	v_cvt_pk_bf16_f32 v19, v20, v21
	v_cvt_pk_bf16_f32 v20, v10, v11
	v_cvt_pk_bf16_f32 v21, v12, v13
	global_store_dwordx4 v[34:35], v[18:21], off offset:256
	v_cvt_pk_bf16_f32 v10, v22, v23
	v_cvt_pk_bf16_f32 v11, v24, v25
	v_cvt_pk_bf16_f32 v12, v14, v15
	v_add_co_u32_e32 v14, vcc, s79, v144
	s_nop 0
	v_lshl_add_u64 v[18:19], v[144:145], 0, s[36:37]
	v_addc_co_u32_e32 v15, vcc, 0, v145, vcc
	s_and_b64 vcc, exec, s[6:7]
	v_cvt_pk_bf16_f32 v13, v16, v17
	global_store_dwordx4 v[14:15], v[10:13], off
	v_cvt_pk_bf16_f32 v6, v6, v7
	v_cvt_pk_bf16_f32 v7, v8, v9
	v_cvt_pk_bf16_f32 v8, v2, v3
	v_cvt_pk_bf16_f32 v9, v4, v5
	global_store_dwordx4 v[18:19], v[6:9], off offset:256
	s_cbranch_vccz .LBB0_2478
	s_waitcnt vmcnt(0)
	s_cmpk_gt_u32 s66, 0xff
	s_cbranch_scc1 .LBB0_2489
	s_barrier

.LBB0_3048:
	s_add_u32 s28, s38, 0xfff00080
	s_addc_u32 s29, s39, -1
	s_cmp_eq_u32 s72, 60
	s_cselect_b32 s45, s37, s29
	s_cselect_b32 s44, s36, s28
	s_cselect_b32 s41, s35, s71
	s_cselect_b32 s40, s34, s21
	v_lshl_add_u64 v[146:147], s[38:39], 0, v[142:143]
	s_add_i32 m0, s23, 0xc000
	s_nop 0
	global_load_lds_dwordx4 v[146:147], off
	v_lshl_add_u64 v[146:147], s[38:39], 0, v[140:141]
	s_add_i32 m0, s23, 0xe000
	s_nop 0
	global_load_lds_dwordx4 v[146:147], off
	ds_read_b128 v[154:157], v150
	ds_read_b128 v[158:161], v150 offset:1024
	ds_read_b128 v[162:165], v150 offset:2048
	ds_read_b128 v[166:169], v150 offset:3072
	ds_read_b128 v[202:205], v152
	ds_read_b128 v[206:209], v152 offset:1024
	ds_read_b128 v[210:213], v152 offset:2048
	ds_read_b128 v[214:217], v152 offset:3072
	ds_read_b128 v[170:173], v151
	ds_read_b128 v[174:177], v151 offset:1024
	ds_read_b128 v[178:181], v151 offset:2048
	ds_read_b128 v[182:185], v151 offset:3072
	ds_read_b128 v[186:189], v151 offset:4096
	ds_read_b128 v[190:193], v151 offset:5120
	ds_read_b128 v[194:197], v151 offset:6144
	ds_read_b128 v[198:201], v151 offset:7168
	s_waitcnt vmcnt(8)
	s_waitcnt lgkmcnt(0)
	s_barrier
	s_setprio 1
	v_mfma_f32_16x16x32_bf16 v[126:129], v[154:157], v[170:173], v[126:129]
	v_mfma_f32_16x16x32_bf16 v[122:125], v[162:165], v[170:173], v[122:125]
	v_mfma_f32_16x16x32_bf16 v[118:121], v[154:157], v[178:181], v[118:121]
	v_mfma_f32_16x16x32_bf16 v[110:113], v[162:165], v[178:181], v[110:113]
	v_mfma_f32_16x16x32_bf16 v[102:105], v[154:157], v[186:189], v[102:105]
	v_mfma_f32_16x16x32_bf16 v[94:97], v[162:165], v[186:189], v[94:97]
	v_mfma_f32_16x16x32_bf16 v[86:89], v[154:157], v[194:197], v[86:89]
	v_mfma_f32_16x16x32_bf16 v[78:81], v[162:165], v[194:197], v[78:81]
	v_mfma_f32_16x16x32_bf16 v[126:129], v[158:161], v[174:177], v[126:129]
	v_mfma_f32_16x16x32_bf16 v[122:125], v[166:169], v[174:177], v[122:125]
	v_mfma_f32_16x16x32_bf16 v[118:121], v[158:161], v[182:185], v[118:121]
	v_mfma_f32_16x16x32_bf16 v[110:113], v[166:169], v[182:185], v[110:113]
	v_mfma_f32_16x16x32_bf16 v[102:105], v[158:161], v[190:193], v[102:105]
	v_mfma_f32_16x16x32_bf16 v[94:97], v[166:169], v[190:193], v[94:97]
	v_mfma_f32_16x16x32_bf16 v[86:89], v[158:161], v[198:201], v[86:89]
	v_mfma_f32_16x16x32_bf16 v[78:81], v[166:169], v[198:201], v[78:81]
	v_mfma_f32_16x16x32_bf16 v[114:117], v[202:205], v[170:173], v[114:117]
	v_mfma_f32_16x16x32_bf16 v[106:109], v[210:213], v[170:173], v[106:109]
	v_mfma_f32_16x16x32_bf16 v[98:101], v[202:205], v[178:181], v[98:101]
	v_mfma_f32_16x16x32_bf16 v[90:93], v[210:213], v[178:181], v[90:93]
	v_mfma_f32_16x16x32_bf16 v[82:85], v[202:205], v[186:189], v[82:85]
	v_mfma_f32_16x16x32_bf16 v[74:77], v[210:213], v[186:189], v[74:77]
	v_mfma_f32_16x16x32_bf16 v[70:73], v[202:205], v[194:197], v[70:73]
	v_mfma_f32_16x16x32_bf16 v[66:69], v[210:213], v[194:197], v[66:69]
	v_mfma_f32_16x16x32_bf16 v[114:117], v[206:209], v[174:177], v[114:117]
	v_mfma_f32_16x16x32_bf16 v[106:109], v[214:217], v[174:177], v[106:109]
	v_mfma_f32_16x16x32_bf16 v[98:101], v[206:209], v[182:185], v[98:101]
	v_mfma_f32_16x16x32_bf16 v[90:93], v[214:217], v[182:185], v[90:93]
	v_mfma_f32_16x16x32_bf16 v[82:85], v[206:209], v[190:193], v[82:85]
	v_mfma_f32_16x16x32_bf16 v[74:77], v[214:217], v[190:193], v[74:77]
	v_mfma_f32_16x16x32_bf16 v[70:73], v[206:209], v[198:201], v[70:73]
	v_mfma_f32_16x16x32_bf16 v[66:69], v[214:217], v[198:201], v[66:69]
	s_setprio 0
	s_barrier
	s_add_i32 s28, s64, s54
	v_lshl_add_u64 v[146:147], s[40:41], 0, v[134:135]
	s_mov_b32 m0, s28
	s_nop 0
	global_load_lds_dwordx4 v[146:147], off
	v_lshl_add_u64 v[218:219], s[40:41], 0, v[130:131]
	s_add_i32 m0, s28, 0x2000
	s_nop 0
	global_load_lds_dwordx4 v[218:219], off
	s_mov_b32 m0, s23
	v_lshl_add_u64 v[220:221], s[44:45], 0, v[136:137]
	global_load_lds_dwordx4 v[220:221], off
	v_lshl_add_u64 v[222:223], s[44:45], 0, v[132:133]
	s_mov_b32 m0, s27
	s_nop 0
	global_load_lds_dwordx4 v[222:223], off
	s_add_u32 s28, s40, 0x100000
	s_addc_u32 s29, s41, 0
	s_add_i32 s73, s65, s54
	v_lshl_add_u64 v[226:227], s[28:29], 0, v[134:135]
	s_mov_b32 m0, s73
	s_nop 0
	global_load_lds_dwordx4 v[226:227], off
	v_lshl_add_u64 v[226:227], s[28:29], 0, v[130:131]
	s_add_i32 m0, s73, 0x2000
	s_nop 0
	global_load_lds_dwordx4 v[226:227], off
	ds_read_b128 v[170:173], v151 offset:16384
	ds_read_b128 v[174:177], v151 offset:17408
	ds_read_b128 v[178:181], v151 offset:18432
	ds_read_b128 v[182:185], v151 offset:19456
	ds_read_b128 v[186:189], v151 offset:20480
	ds_read_b128 v[190:193], v151 offset:21504
	ds_read_b128 v[194:197], v151 offset:22528
	ds_read_b128 v[198:201], v151 offset:23552
	s_waitcnt vmcnt(8)
	s_waitcnt lgkmcnt(0)
	s_barrier
	s_setprio 1
	v_mfma_f32_16x16x32_bf16 v[62:65], v[154:157], v[170:173], v[62:65]
	v_mfma_f32_16x16x32_bf16 v[58:61], v[162:165], v[170:173], v[58:61]
	v_mfma_f32_16x16x32_bf16 v[54:57], v[154:157], v[178:181], v[54:57]
	v_mfma_f32_16x16x32_bf16 v[46:49], v[162:165], v[178:181], v[46:49]
	v_mfma_f32_16x16x32_bf16 v[38:41], v[154:157], v[186:189], v[38:41]
	v_mfma_f32_16x16x32_bf16 v[30:33], v[162:165], v[186:189], v[30:33]
	v_mfma_f32_16x16x32_bf16 v[22:25], v[154:157], v[194:197], v[22:25]
	v_mfma_f32_16x16x32_bf16 v[14:17], v[162:165], v[194:197], v[14:17]
	v_mfma_f32_16x16x32_bf16 v[62:65], v[158:161], v[174:177], v[62:65]
	v_mfma_f32_16x16x32_bf16 v[58:61], v[166:169], v[174:177], v[58:61]
	v_mfma_f32_16x16x32_bf16 v[54:57], v[158:161], v[182:185], v[54:57]
	v_mfma_f32_16x16x32_bf16 v[46:49], v[166:169], v[182:185], v[46:49]
	v_mfma_f32_16x16x32_bf16 v[38:41], v[158:161], v[190:193], v[38:41]
	v_mfma_f32_16x16x32_bf16 v[30:33], v[166:169], v[190:193], v[30:33]
	v_mfma_f32_16x16x32_bf16 v[22:25], v[158:161], v[198:201], v[22:25]
	v_mfma_f32_16x16x32_bf16 v[14:17], v[166:169], v[198:201], v[14:17]
	v_mfma_f32_16x16x32_bf16 v[50:53], v[202:205], v[170:173], v[50:53]
	v_mfma_f32_16x16x32_bf16 v[42:45], v[210:213], v[170:173], v[42:45]
	v_mfma_f32_16x16x32_bf16 v[34:37], v[202:205], v[178:181], v[34:37]
	v_mfma_f32_16x16x32_bf16 v[26:29], v[210:213], v[178:181], v[26:29]
	v_mfma_f32_16x16x32_bf16 v[18:21], v[202:205], v[186:189], v[18:21]
	v_mfma_f32_16x16x32_bf16 v[10:13], v[210:213], v[186:189], v[10:13]
	v_mfma_f32_16x16x32_bf16 v[6:9], v[202:205], v[194:197], v[6:9]
	v_mfma_f32_16x16x32_bf16 v[2:5], v[210:213], v[194:197], v[2:5]
	v_mfma_f32_16x16x32_bf16 v[50:53], v[206:209], v[174:177], v[50:53]
	v_mfma_f32_16x16x32_bf16 v[42:45], v[214:217], v[174:177], v[42:45]
	v_mfma_f32_16x16x32_bf16 v[34:37], v[206:209], v[182:185], v[34:37]
	v_mfma_f32_16x16x32_bf16 v[26:29], v[214:217], v[182:185], v[26:29]
	v_mfma_f32_16x16x32_bf16 v[18:21], v[206:209], v[190:193], v[18:21]
	v_mfma_f32_16x16x32_bf16 v[10:13], v[214:217], v[190:193], v[10:13]
	v_mfma_f32_16x16x32_bf16 v[6:9], v[206:209], v[198:201], v[6:9]
	v_mfma_f32_16x16x32_bf16 v[2:5], v[214:217], v[198:201], v[2:5]
	s_setprio 0
	s_add_i32 s73, 0, 0x18000
	v_add_u32_e32 v153, s73, v148
	s_barrier
	s_add_u32 s28, s44, 0x100000
	s_addc_u32 s29, s45, 0
	s_mov_b32 m0, s55
	v_lshl_add_u64 v[226:227], s[28:29], 0, v[136:137]
	global_load_lds_dwordx4 v[226:227], off
	v_lshl_add_u64 v[226:227], s[28:29], 0, v[132:133]
	s_mov_b32 m0, s56
	s_nop 0
	global_load_lds_dwordx4 v[226:227], off
	ds_read_b128 v[154:157], v153
	ds_read_b128 v[158:161], v153 offset:1024
	ds_read_b128 v[162:165], v153 offset:2048
	ds_read_b128 v[166:169], v153 offset:3072
	ds_read_b128 v[202:205], v153 offset:16384
	ds_read_b128 v[206:209], v153 offset:17408
	ds_read_b128 v[210:213], v153 offset:18432
	ds_read_b128 v[214:217], v153 offset:19456
	ds_read_b128 v[170:173], v151 offset:32768
	ds_read_b128 v[174:177], v151 offset:33792
	ds_read_b128 v[178:181], v151 offset:34816
	ds_read_b128 v[182:185], v151 offset:35840
	ds_read_b128 v[186:189], v151 offset:36864
	ds_read_b128 v[190:193], v151 offset:37888
	ds_read_b128 v[194:197], v151 offset:38912
	ds_read_b128 v[198:201], v151 offset:39936
	s_waitcnt vmcnt(8)
	s_waitcnt lgkmcnt(0)
	s_barrier
	s_setprio 1
	v_mfma_f32_16x16x32_bf16 v[126:129], v[154:157], v[170:173], v[126:129]
	v_mfma_f32_16x16x32_bf16 v[122:125], v[162:165], v[170:173], v[122:125]
	v_mfma_f32_16x16x32_bf16 v[118:121], v[154:157], v[178:181], v[118:121]
	v_mfma_f32_16x16x32_bf16 v[110:113], v[162:165], v[178:181], v[110:113]
	v_mfma_f32_16x16x32_bf16 v[102:105], v[154:157], v[186:189], v[102:105]
	v_mfma_f32_16x16x32_bf16 v[94:97], v[162:165], v[186:189], v[94:97]
	v_mfma_f32_16x16x32_bf16 v[86:89], v[154:157], v[194:197], v[86:89]
	v_mfma_f32_16x16x32_bf16 v[78:81], v[162:165], v[194:197], v[78:81]
	v_mfma_f32_16x16x32_bf16 v[126:129], v[158:161], v[174:177], v[126:129]
	v_mfma_f32_16x16x32_bf16 v[122:125], v[166:169], v[174:177], v[122:125]
	v_mfma_f32_16x16x32_bf16 v[118:121], v[158:161], v[182:185], v[118:121]
	v_mfma_f32_16x16x32_bf16 v[110:113], v[166:169], v[182:185], v[110:113]
	v_mfma_f32_16x16x32_bf16 v[102:105], v[158:161], v[190:193], v[102:105]
	v_mfma_f32_16x16x32_bf16 v[94:97], v[166:169], v[190:193], v[94:97]
	v_mfma_f32_16x16x32_bf16 v[86:89], v[158:161], v[198:201], v[86:89]
	v_mfma_f32_16x16x32_bf16 v[78:81], v[166:169], v[198:201], v[78:81]
	v_mfma_f32_16x16x32_bf16 v[114:117], v[202:205], v[170:173], v[114:117]
	v_mfma_f32_16x16x32_bf16 v[106:109], v[210:213], v[170:173], v[106:109]
	v_mfma_f32_16x16x32_bf16 v[98:101], v[202:205], v[178:181], v[98:101]
	v_mfma_f32_16x16x32_bf16 v[90:93], v[210:213], v[178:181], v[90:93]
	v_mfma_f32_16x16x32_bf16 v[82:85], v[202:205], v[186:189], v[82:85]
	v_mfma_f32_16x16x32_bf16 v[74:77], v[210:213], v[186:189], v[74:77]
	v_mfma_f32_16x16x32_bf16 v[70:73], v[202:205], v[194:197], v[70:73]
	v_mfma_f32_16x16x32_bf16 v[66:69], v[210:213], v[194:197], v[66:69]
	v_mfma_f32_16x16x32_bf16 v[114:117], v[206:209], v[174:177], v[114:117]
	v_mfma_f32_16x16x32_bf16 v[106:109], v[214:217], v[174:177], v[106:109]
	v_mfma_f32_16x16x32_bf16 v[98:101], v[206:209], v[182:185], v[98:101]
	v_mfma_f32_16x16x32_bf16 v[90:93], v[214:217], v[182:185], v[90:93]
	v_mfma_f32_16x16x32_bf16 v[82:85], v[206:209], v[190:193], v[82:85]
	v_mfma_f32_16x16x32_bf16 v[74:77], v[214:217], v[190:193], v[74:77]
	v_mfma_f32_16x16x32_bf16 v[70:73], v[206:209], v[198:201], v[70:73]
	v_mfma_f32_16x16x32_bf16 v[66:69], v[214:217], v[198:201], v[66:69]
	s_setprio 0
	s_barrier
	s_add_i32 s44, 0, 0x1c000
	s_add_i32 s28, s73, s54
	v_lshl_add_u64 v[146:147], v[146:147], 0, s[6:7]
	s_mov_b32 m0, s28
	s_nop 0
	global_load_lds_dwordx4 v[146:147], off
	v_lshl_add_u64 v[146:147], v[218:219], 0, s[6:7]
	s_add_i32 m0, s28, 0x2000
	s_nop 0
	global_load_lds_dwordx4 v[146:147], off
	s_mov_b32 m0, s59
	v_lshl_add_u64 v[146:147], v[220:221], 0, s[6:7]
	global_load_lds_dwordx4 v[146:147], off
	v_lshl_add_u64 v[146:147], v[222:223], 0, s[6:7]
	s_mov_b32 m0, s60
	s_nop 0
	global_load_lds_dwordx4 v[146:147], off
	s_add_u32 s28, s40, 0x100080
	s_addc_u32 s29, s41, 0
	s_add_i32 s40, s44, s54
	v_lshl_add_u64 v[146:147], s[28:29], 0, v[134:135]
	s_mov_b32 m0, s40
	s_nop 0
	global_load_lds_dwordx4 v[146:147], off
	v_lshl_add_u64 v[146:147], s[28:29], 0, v[130:131]
	s_add_i32 m0, s40, 0x2000
	s_nop 0
	global_load_lds_dwordx4 v[146:147], off
	ds_read_b128 v[170:173], v151 offset:49152
	ds_read_b128 v[174:177], v151 offset:50176
	ds_read_b128 v[178:181], v151 offset:51200
	ds_read_b128 v[182:185], v151 offset:52224
	ds_read_b128 v[186:189], v151 offset:53248
	ds_read_b128 v[190:193], v151 offset:54272
	ds_read_b128 v[194:197], v151 offset:55296
	ds_read_b128 v[198:201], v151 offset:56320
	s_waitcnt vmcnt(8)
	s_waitcnt lgkmcnt(0)
	s_barrier
	s_setprio 1
	v_mfma_f32_16x16x32_bf16 v[62:65], v[154:157], v[170:173], v[62:65]
	v_mfma_f32_16x16x32_bf16 v[58:61], v[162:165], v[170:173], v[58:61]
	v_mfma_f32_16x16x32_bf16 v[54:57], v[154:157], v[178:181], v[54:57]
	v_mfma_f32_16x16x32_bf16 v[46:49], v[162:165], v[178:181], v[46:49]
	v_mfma_f32_16x16x32_bf16 v[38:41], v[154:157], v[186:189], v[38:41]
	v_mfma_f32_16x16x32_bf16 v[30:33], v[162:165], v[186:189], v[30:33]
	v_mfma_f32_16x16x32_bf16 v[22:25], v[154:157], v[194:197], v[22:25]
	v_mfma_f32_16x16x32_bf16 v[14:17], v[162:165], v[194:197], v[14:17]
	v_mfma_f32_16x16x32_bf16 v[62:65], v[158:161], v[174:177], v[62:65]
	v_mfma_f32_16x16x32_bf16 v[58:61], v[166:169], v[174:177], v[58:61]
	v_mfma_f32_16x16x32_bf16 v[54:57], v[158:161], v[182:185], v[54:57]
	v_mfma_f32_16x16x32_bf16 v[46:49], v[166:169], v[182:185], v[46:49]
	v_mfma_f32_16x16x32_bf16 v[38:41], v[158:161], v[190:193], v[38:41]
	v_mfma_f32_16x16x32_bf16 v[30:33], v[166:169], v[190:193], v[30:33]
	v_mfma_f32_16x16x32_bf16 v[22:25], v[158:161], v[198:201], v[22:25]
	v_mfma_f32_16x16x32_bf16 v[14:17], v[166:169], v[198:201], v[14:17]
	v_mfma_f32_16x16x32_bf16 v[50:53], v[202:205], v[170:173], v[50:53]
	v_mfma_f32_16x16x32_bf16 v[42:45], v[210:213], v[170:173], v[42:45]
	v_mfma_f32_16x16x32_bf16 v[34:37], v[202:205], v[178:181], v[34:37]
	v_mfma_f32_16x16x32_bf16 v[26:29], v[210:213], v[178:181], v[26:29]
	v_mfma_f32_16x16x32_bf16 v[18:21], v[202:205], v[186:189], v[18:21]
	v_mfma_f32_16x16x32_bf16 v[10:13], v[210:213], v[186:189], v[10:13]
	v_mfma_f32_16x16x32_bf16 v[6:9], v[202:205], v[194:197], v[6:9]
	v_mfma_f32_16x16x32_bf16 v[2:5], v[210:213], v[194:197], v[2:5]
	v_mfma_f32_16x16x32_bf16 v[50:53], v[206:209], v[174:177], v[50:53]
	v_mfma_f32_16x16x32_bf16 v[42:45], v[214:217], v[174:177], v[42:45]
	v_mfma_f32_16x16x32_bf16 v[34:37], v[206:209], v[182:185], v[34:37]
	v_mfma_f32_16x16x32_bf16 v[26:29], v[214:217], v[182:185], v[26:29]
	v_mfma_f32_16x16x32_bf16 v[18:21], v[206:209], v[190:193], v[18:21]
	v_mfma_f32_16x16x32_bf16 v[10:13], v[214:217], v[190:193], v[10:13]
	v_mfma_f32_16x16x32_bf16 v[6:9], v[206:209], v[198:201], v[6:9]
	v_mfma_f32_16x16x32_bf16 v[2:5], v[214:217], v[198:201], v[2:5]
	s_setprio 0
	s_add_i32 s72, s72, 2
	s_add_u32 s21, s21, 0x100
	s_addc_u32 s71, s71, 0
	s_add_u32 s38, s38, 0x100
	s_addc_u32 s39, s39, 0
	s_cmp_gt_u32 s72, 61
	s_barrier
	s_cbranch_scc0 .LBB0_3048
	s_cmp_lt_i32 s70, 2
	s_cbranch_scc1 .LBB0_3053
	s_cmp_eq_u32 s70, 2
	s_mov_b64 s[38:39], -1
	s_cbranch_scc0 .LBB0_3052
	v_lshl_add_u32 v146, s26, 8, v1
	v_or_b32_e32 v156, 16, v146
	v_ashrrev_i32_e32 v147, 31, v146
	v_ashrrev_i32_e32 v157, 31, v156
	v_lshlrev_b64 v[154:155], 10, v[146:147]
	v_lshlrev_b64 v[156:157], 10, v[156:157]
	v_lshl_add_u64 v[154:155], v[138:139], 0, v[154:155]
	v_lshl_add_u64 v[156:157], v[138:139], 0, v[156:157]
	global_store_dwordx4 v[154:155], v[126:129], off
	global_store_dwordx4 v[154:155], v[122:125], off offset:16
	global_store_dwordx4 v[154:155], v[114:117], off offset:512
	global_store_dwordx4 v[154:155], v[106:109], off offset:528
	global_store_dwordx4 v[156:157], v[118:121], off
	global_store_dwordx4 v[156:157], v[110:113], off offset:16
	global_store_dwordx4 v[156:157], v[98:101], off offset:512
	global_store_dwordx4 v[156:157], v[90:93], off offset:528
	v_or_b32_e32 v156, 32, v146
	v_ashrrev_i32_e32 v157, 31, v156
	v_lshlrev_b64 v[156:157], 10, v[156:157]
	v_or_b32_e32 v146, 48, v146
	v_lshl_add_u64 v[156:157], v[138:139], 0, v[156:157]
	v_ashrrev_i32_e32 v147, 31, v146
	global_store_dwordx4 v[156:157], v[102:105], off
	global_store_dwordx4 v[156:157], v[94:97], off offset:16
	global_store_dwordx4 v[156:157], v[82:85], off offset:512
	global_store_dwordx4 v[156:157], v[74:77], off offset:528
	v_lshlrev_b64 v[146:147], 10, v[146:147]
	v_add_co_u32_e32 v156, vcc, s66, v154
	v_lshl_add_u64 v[146:147], v[138:139], 0, v[146:147]
	s_nop 0
	v_addc_co_u32_e32 v157, vcc, 0, v155, vcc
	global_store_dwordx4 v[146:147], v[86:89], off
	global_store_dwordx4 v[146:147], v[78:81], off offset:16
	global_store_dwordx4 v[146:147], v[70:73], off offset:512
	global_store_dwordx4 v[146:147], v[66:69], off offset:528
	v_lshl_add_u64 v[146:147], v[154:155], 0, s[8:9]
	global_store_dwordx4 v[156:157], v[62:65], off
	global_store_dwordx4 v[146:147], v[58:61], off offset:16
	global_store_dwordx4 v[146:147], v[50:53], off offset:512
	global_store_dwordx4 v[146:147], v[42:45], off offset:528
	v_add_co_u32_e32 v156, vcc, s67, v154
	v_lshl_add_u64 v[146:147], v[154:155], 0, s[12:13]
	s_nop 0
	v_addc_co_u32_e32 v157, vcc, 0, v155, vcc
	global_store_dwordx4 v[156:157], v[54:57], off
	global_store_dwordx4 v[146:147], v[46:49], off offset:16
	global_store_dwordx4 v[146:147], v[34:37], off offset:512
	global_store_dwordx4 v[146:147], v[26:29], off offset:528
	v_add_co_u32_e32 v156, vcc, s68, v154
	v_lshl_add_u64 v[146:147], v[154:155], 0, s[14:15]
	s_nop 0
	v_addc_co_u32_e32 v157, vcc, 0, v155, vcc
	global_store_dwordx4 v[156:157], v[38:41], off
	global_store_dwordx4 v[146:147], v[30:33], off offset:16
	global_store_dwordx4 v[146:147], v[18:21], off offset:512
	global_store_dwordx4 v[146:147], v[10:13], off offset:528
	v_lshl_add_u64 v[146:147], v[154:155], 0, s[16:17]
	v_add_co_u32_e32 v154, vcc, 0x2c000, v154
	s_mov_b64 s[38:39], 0
	s_nop 0
	v_addc_co_u32_e32 v155, vcc, 0, v155, vcc
	global_store_dwordx4 v[154:155], v[22:25], off
	global_store_dwordx4 v[146:147], v[14:17], off offset:16
	global_store_dwordx4 v[146:147], v[6:9], off offset:512
	global_store_dwordx4 v[146:147], v[2:5], off offset:528

.LBB0_4133:
	s_add_u32 s28, s38, 0xfff00080
	s_addc_u32 s29, s39, -1
	s_cmp_eq_u32 s60, 60
	s_cselect_b32 s45, s27, s29
	s_cselect_b32 s44, s26, s28
	s_cselect_b32 s41, s35, s23
	s_cselect_b32 s40, s34, s21
	v_lshl_add_u64 v[144:145], s[38:39], 0, v[140:141]
	s_add_i32 m0, s37, 0xc000
	s_nop 0
	global_load_lds_dwordx4 v[144:145], off
	v_lshl_add_u64 v[144:145], s[38:39], 0, v[138:139]
	s_add_i32 m0, s37, 0xe000
	s_nop 0
	global_load_lds_dwordx4 v[144:145], off
	ds_read_b128 v[152:155], v148
	ds_read_b128 v[156:159], v148 offset:1024
	ds_read_b128 v[160:163], v148 offset:2048
	ds_read_b128 v[164:167], v148 offset:3072
	ds_read_b128 v[200:203], v150
	ds_read_b128 v[204:207], v150 offset:1024
	ds_read_b128 v[208:211], v150 offset:2048
	ds_read_b128 v[212:215], v150 offset:3072
	ds_read_b128 v[168:171], v149
	ds_read_b128 v[172:175], v149 offset:1024
	ds_read_b128 v[176:179], v149 offset:2048
	ds_read_b128 v[180:183], v149 offset:3072
	ds_read_b128 v[184:187], v149 offset:4096
	ds_read_b128 v[188:191], v149 offset:5120
	ds_read_b128 v[192:195], v149 offset:6144
	ds_read_b128 v[196:199], v149 offset:7168
	s_waitcnt vmcnt(8)
	s_waitcnt lgkmcnt(0)
	s_barrier
	s_setprio 1
	v_mfma_f32_16x16x32_bf16 v[126:129], v[152:155], v[168:171], v[126:129]
	v_mfma_f32_16x16x32_bf16 v[122:125], v[160:163], v[168:171], v[122:125]
	v_mfma_f32_16x16x32_bf16 v[114:117], v[152:155], v[176:179], v[114:117]
	v_mfma_f32_16x16x32_bf16 v[106:109], v[160:163], v[176:179], v[106:109]
	v_mfma_f32_16x16x32_bf16 v[98:101], v[152:155], v[184:187], v[98:101]
	v_mfma_f32_16x16x32_bf16 v[90:93], v[160:163], v[184:187], v[90:93]
	v_mfma_f32_16x16x32_bf16 v[82:85], v[152:155], v[192:195], v[82:85]
	v_mfma_f32_16x16x32_bf16 v[74:77], v[160:163], v[192:195], v[74:77]
	v_mfma_f32_16x16x32_bf16 v[126:129], v[156:159], v[172:175], v[126:129]
	v_mfma_f32_16x16x32_bf16 v[122:125], v[164:167], v[172:175], v[122:125]
	v_mfma_f32_16x16x32_bf16 v[114:117], v[156:159], v[180:183], v[114:117]
	v_mfma_f32_16x16x32_bf16 v[106:109], v[164:167], v[180:183], v[106:109]
	v_mfma_f32_16x16x32_bf16 v[98:101], v[156:159], v[188:191], v[98:101]
	v_mfma_f32_16x16x32_bf16 v[90:93], v[164:167], v[188:191], v[90:93]
	v_mfma_f32_16x16x32_bf16 v[82:85], v[156:159], v[196:199], v[82:85]
	v_mfma_f32_16x16x32_bf16 v[74:77], v[164:167], v[196:199], v[74:77]
	v_mfma_f32_16x16x32_bf16 v[118:121], v[200:203], v[168:171], v[118:121]
	v_mfma_f32_16x16x32_bf16 v[110:113], v[208:211], v[168:171], v[110:113]
	v_mfma_f32_16x16x32_bf16 v[102:105], v[200:203], v[176:179], v[102:105]
	v_mfma_f32_16x16x32_bf16 v[94:97], v[208:211], v[176:179], v[94:97]
	v_mfma_f32_16x16x32_bf16 v[86:89], v[200:203], v[184:187], v[86:89]
	v_mfma_f32_16x16x32_bf16 v[78:81], v[208:211], v[184:187], v[78:81]
	v_mfma_f32_16x16x32_bf16 v[70:73], v[200:203], v[192:195], v[70:73]
	v_mfma_f32_16x16x32_bf16 v[66:69], v[208:211], v[192:195], v[66:69]
	v_mfma_f32_16x16x32_bf16 v[118:121], v[204:207], v[172:175], v[118:121]
	v_mfma_f32_16x16x32_bf16 v[110:113], v[212:215], v[172:175], v[110:113]
	v_mfma_f32_16x16x32_bf16 v[102:105], v[204:207], v[180:183], v[102:105]
	v_mfma_f32_16x16x32_bf16 v[94:97], v[212:215], v[180:183], v[94:97]
	v_mfma_f32_16x16x32_bf16 v[86:89], v[204:207], v[188:191], v[86:89]
	v_mfma_f32_16x16x32_bf16 v[78:81], v[212:215], v[188:191], v[78:81]
	v_mfma_f32_16x16x32_bf16 v[70:73], v[204:207], v[196:199], v[70:73]
	v_mfma_f32_16x16x32_bf16 v[66:69], v[212:215], v[196:199], v[66:69]
	s_setprio 0
	s_barrier
	s_add_i32 s28, s53, s31
	v_lshl_add_u64 v[144:145], s[40:41], 0, v[134:135]
	s_mov_b32 m0, s28
	s_nop 0
	global_load_lds_dwordx4 v[144:145], off
	v_lshl_add_u64 v[216:217], s[40:41], 0, v[130:131]
	s_add_i32 m0, s28, 0x2000
	s_nop 0
	global_load_lds_dwordx4 v[216:217], off
	s_mov_b32 m0, s37
	v_lshl_add_u64 v[218:219], s[44:45], 0, v[136:137]
	global_load_lds_dwordx4 v[218:219], off
	v_lshl_add_u64 v[220:221], s[44:45], 0, v[132:133]
	s_mov_b32 m0, s46
	s_nop 0
	global_load_lds_dwordx4 v[220:221], off
	s_add_u32 s28, s40, 0x100000
	s_addc_u32 s29, s41, 0
	s_add_i32 s61, s54, s31
	v_lshl_add_u64 v[226:227], s[28:29], 0, v[134:135]
	s_mov_b32 m0, s61
	s_nop 0
	global_load_lds_dwordx4 v[226:227], off
	v_lshl_add_u64 v[226:227], s[28:29], 0, v[130:131]
	s_add_i32 m0, s61, 0x2000
	s_nop 0
	global_load_lds_dwordx4 v[226:227], off
	ds_read_b128 v[168:171], v149 offset:16384
	ds_read_b128 v[172:175], v149 offset:17408
	ds_read_b128 v[176:179], v149 offset:18432
	ds_read_b128 v[180:183], v149 offset:19456
	ds_read_b128 v[184:187], v149 offset:20480
	ds_read_b128 v[188:191], v149 offset:21504
	ds_read_b128 v[192:195], v149 offset:22528
	ds_read_b128 v[196:199], v149 offset:23552
	s_waitcnt vmcnt(8)
	s_waitcnt lgkmcnt(0)
	s_barrier
	s_setprio 1
	v_mfma_f32_16x16x32_bf16 v[62:65], v[152:155], v[168:171], v[62:65]
	v_mfma_f32_16x16x32_bf16 v[58:61], v[160:163], v[168:171], v[58:61]
	v_mfma_f32_16x16x32_bf16 v[54:57], v[152:155], v[176:179], v[54:57]
	v_mfma_f32_16x16x32_bf16 v[46:49], v[160:163], v[176:179], v[46:49]
	v_mfma_f32_16x16x32_bf16 v[38:41], v[152:155], v[184:187], v[38:41]
	v_mfma_f32_16x16x32_bf16 v[30:33], v[160:163], v[184:187], v[30:33]
	v_mfma_f32_16x16x32_bf16 v[22:25], v[152:155], v[192:195], v[22:25]
	v_mfma_f32_16x16x32_bf16 v[14:17], v[160:163], v[192:195], v[14:17]
	v_mfma_f32_16x16x32_bf16 v[62:65], v[156:159], v[172:175], v[62:65]
	v_mfma_f32_16x16x32_bf16 v[58:61], v[164:167], v[172:175], v[58:61]
	v_mfma_f32_16x16x32_bf16 v[54:57], v[156:159], v[180:183], v[54:57]
	v_mfma_f32_16x16x32_bf16 v[46:49], v[164:167], v[180:183], v[46:49]
	v_mfma_f32_16x16x32_bf16 v[38:41], v[156:159], v[188:191], v[38:41]
	v_mfma_f32_16x16x32_bf16 v[30:33], v[164:167], v[188:191], v[30:33]
	v_mfma_f32_16x16x32_bf16 v[22:25], v[156:159], v[196:199], v[22:25]
	v_mfma_f32_16x16x32_bf16 v[14:17], v[164:167], v[196:199], v[14:17]
	v_mfma_f32_16x16x32_bf16 v[50:53], v[200:203], v[168:171], v[50:53]
	v_mfma_f32_16x16x32_bf16 v[42:45], v[208:211], v[168:171], v[42:45]
	v_mfma_f32_16x16x32_bf16 v[34:37], v[200:203], v[176:179], v[34:37]
	v_mfma_f32_16x16x32_bf16 v[26:29], v[208:211], v[176:179], v[26:29]
	v_mfma_f32_16x16x32_bf16 v[18:21], v[200:203], v[184:187], v[18:21]
	v_mfma_f32_16x16x32_bf16 v[10:13], v[208:211], v[184:187], v[10:13]
	v_mfma_f32_16x16x32_bf16 v[6:9], v[200:203], v[192:195], v[6:9]
	v_mfma_f32_16x16x32_bf16 v[2:5], v[208:211], v[192:195], v[2:5]
	v_mfma_f32_16x16x32_bf16 v[50:53], v[204:207], v[172:175], v[50:53]
	v_mfma_f32_16x16x32_bf16 v[42:45], v[212:215], v[172:175], v[42:45]
	v_mfma_f32_16x16x32_bf16 v[34:37], v[204:207], v[180:183], v[34:37]
	v_mfma_f32_16x16x32_bf16 v[26:29], v[212:215], v[180:183], v[26:29]
	v_mfma_f32_16x16x32_bf16 v[18:21], v[204:207], v[188:191], v[18:21]
	v_mfma_f32_16x16x32_bf16 v[10:13], v[212:215], v[188:191], v[10:13]
	v_mfma_f32_16x16x32_bf16 v[6:9], v[204:207], v[196:199], v[6:9]
	v_mfma_f32_16x16x32_bf16 v[2:5], v[212:215], v[196:199], v[2:5]
	s_setprio 0
	s_add_i32 s61, 0, 0x18000
	v_add_u32_e32 v151, s61, v146
	s_barrier
	s_add_u32 s28, s44, 0x100000
	s_addc_u32 s29, s45, 0
	s_mov_b32 m0, s47
	v_lshl_add_u64 v[226:227], s[28:29], 0, v[136:137]
	global_load_lds_dwordx4 v[226:227], off
	v_lshl_add_u64 v[226:227], s[28:29], 0, v[132:133]
	s_mov_b32 m0, s48
	s_nop 0
	global_load_lds_dwordx4 v[226:227], off
	ds_read_b128 v[152:155], v151
	ds_read_b128 v[156:159], v151 offset:1024
	ds_read_b128 v[160:163], v151 offset:2048
	ds_read_b128 v[164:167], v151 offset:3072
	ds_read_b128 v[200:203], v151 offset:16384
	ds_read_b128 v[204:207], v151 offset:17408
	ds_read_b128 v[208:211], v151 offset:18432
	ds_read_b128 v[212:215], v151 offset:19456
	ds_read_b128 v[168:171], v149 offset:32768
	ds_read_b128 v[172:175], v149 offset:33792
	ds_read_b128 v[176:179], v149 offset:34816
	ds_read_b128 v[180:183], v149 offset:35840
	ds_read_b128 v[184:187], v149 offset:36864
	ds_read_b128 v[188:191], v149 offset:37888
	ds_read_b128 v[192:195], v149 offset:38912
	ds_read_b128 v[196:199], v149 offset:39936
	s_waitcnt vmcnt(8)
	s_waitcnt lgkmcnt(0)
	s_barrier
	s_setprio 1
	v_mfma_f32_16x16x32_bf16 v[126:129], v[152:155], v[168:171], v[126:129]
	v_mfma_f32_16x16x32_bf16 v[122:125], v[160:163], v[168:171], v[122:125]
	v_mfma_f32_16x16x32_bf16 v[114:117], v[152:155], v[176:179], v[114:117]
	v_mfma_f32_16x16x32_bf16 v[106:109], v[160:163], v[176:179], v[106:109]
	v_mfma_f32_16x16x32_bf16 v[98:101], v[152:155], v[184:187], v[98:101]
	v_mfma_f32_16x16x32_bf16 v[90:93], v[160:163], v[184:187], v[90:93]
	v_mfma_f32_16x16x32_bf16 v[82:85], v[152:155], v[192:195], v[82:85]
	v_mfma_f32_16x16x32_bf16 v[74:77], v[160:163], v[192:195], v[74:77]
	v_mfma_f32_16x16x32_bf16 v[126:129], v[156:159], v[172:175], v[126:129]
	v_mfma_f32_16x16x32_bf16 v[122:125], v[164:167], v[172:175], v[122:125]
	v_mfma_f32_16x16x32_bf16 v[114:117], v[156:159], v[180:183], v[114:117]
	v_mfma_f32_16x16x32_bf16 v[106:109], v[164:167], v[180:183], v[106:109]
	v_mfma_f32_16x16x32_bf16 v[98:101], v[156:159], v[188:191], v[98:101]
	v_mfma_f32_16x16x32_bf16 v[90:93], v[164:167], v[188:191], v[90:93]
	v_mfma_f32_16x16x32_bf16 v[82:85], v[156:159], v[196:199], v[82:85]
	v_mfma_f32_16x16x32_bf16 v[74:77], v[164:167], v[196:199], v[74:77]
	v_mfma_f32_16x16x32_bf16 v[118:121], v[200:203], v[168:171], v[118:121]
	v_mfma_f32_16x16x32_bf16 v[110:113], v[208:211], v[168:171], v[110:113]
	v_mfma_f32_16x16x32_bf16 v[102:105], v[200:203], v[176:179], v[102:105]
	v_mfma_f32_16x16x32_bf16 v[94:97], v[208:211], v[176:179], v[94:97]
	v_mfma_f32_16x16x32_bf16 v[86:89], v[200:203], v[184:187], v[86:89]
	v_mfma_f32_16x16x32_bf16 v[78:81], v[208:211], v[184:187], v[78:81]
	v_mfma_f32_16x16x32_bf16 v[70:73], v[200:203], v[192:195], v[70:73]
	v_mfma_f32_16x16x32_bf16 v[66:69], v[208:211], v[192:195], v[66:69]
	v_mfma_f32_16x16x32_bf16 v[118:121], v[204:207], v[172:175], v[118:121]
	v_mfma_f32_16x16x32_bf16 v[110:113], v[212:215], v[172:175], v[110:113]
	v_mfma_f32_16x16x32_bf16 v[102:105], v[204:207], v[180:183], v[102:105]
	v_mfma_f32_16x16x32_bf16 v[94:97], v[212:215], v[180:183], v[94:97]
	v_mfma_f32_16x16x32_bf16 v[86:89], v[204:207], v[188:191], v[86:89]
	v_mfma_f32_16x16x32_bf16 v[78:81], v[212:215], v[188:191], v[78:81]
	v_mfma_f32_16x16x32_bf16 v[70:73], v[204:207], v[196:199], v[70:73]
	v_mfma_f32_16x16x32_bf16 v[66:69], v[212:215], v[196:199], v[66:69]
	s_setprio 0
	s_barrier
	s_add_i32 s44, 0, 0x1c000
	s_add_i32 s28, s61, s31
	v_lshl_add_u64 v[144:145], v[144:145], 0, s[12:13]
	s_mov_b32 m0, s28
	s_nop 0
	global_load_lds_dwordx4 v[144:145], off
	v_lshl_add_u64 v[144:145], v[216:217], 0, s[12:13]
	s_add_i32 m0, s28, 0x2000
	s_nop 0
	global_load_lds_dwordx4 v[144:145], off
	s_mov_b32 m0, s50
	v_lshl_add_u64 v[144:145], v[218:219], 0, s[12:13]
	global_load_lds_dwordx4 v[144:145], off
	v_lshl_add_u64 v[144:145], v[220:221], 0, s[12:13]
	s_mov_b32 m0, s51
	s_nop 0
	global_load_lds_dwordx4 v[144:145], off
	s_add_u32 s28, s40, 0x100080
	s_addc_u32 s29, s41, 0
	s_add_i32 s40, s44, s31
	v_lshl_add_u64 v[144:145], s[28:29], 0, v[134:135]
	s_mov_b32 m0, s40
	s_nop 0
	global_load_lds_dwordx4 v[144:145], off
	v_lshl_add_u64 v[144:145], s[28:29], 0, v[130:131]
	s_add_i32 m0, s40, 0x2000
	s_nop 0
	global_load_lds_dwordx4 v[144:145], off
	ds_read_b128 v[168:171], v149 offset:49152
	ds_read_b128 v[172:175], v149 offset:50176
	ds_read_b128 v[176:179], v149 offset:51200
	ds_read_b128 v[180:183], v149 offset:52224
	ds_read_b128 v[184:187], v149 offset:53248
	ds_read_b128 v[188:191], v149 offset:54272
	ds_read_b128 v[192:195], v149 offset:55296
	ds_read_b128 v[196:199], v149 offset:56320
	s_waitcnt vmcnt(8)
	s_waitcnt lgkmcnt(0)
	s_barrier
	s_setprio 1
	v_mfma_f32_16x16x32_bf16 v[62:65], v[152:155], v[168:171], v[62:65]
	v_mfma_f32_16x16x32_bf16 v[58:61], v[160:163], v[168:171], v[58:61]
	v_mfma_f32_16x16x32_bf16 v[54:57], v[152:155], v[176:179], v[54:57]
	v_mfma_f32_16x16x32_bf16 v[46:49], v[160:163], v[176:179], v[46:49]
	v_mfma_f32_16x16x32_bf16 v[38:41], v[152:155], v[184:187], v[38:41]
	v_mfma_f32_16x16x32_bf16 v[30:33], v[160:163], v[184:187], v[30:33]
	v_mfma_f32_16x16x32_bf16 v[22:25], v[152:155], v[192:195], v[22:25]
	v_mfma_f32_16x16x32_bf16 v[14:17], v[160:163], v[192:195], v[14:17]
	v_mfma_f32_16x16x32_bf16 v[62:65], v[156:159], v[172:175], v[62:65]
	v_mfma_f32_16x16x32_bf16 v[58:61], v[164:167], v[172:175], v[58:61]
	v_mfma_f32_16x16x32_bf16 v[54:57], v[156:159], v[180:183], v[54:57]
	v_mfma_f32_16x16x32_bf16 v[46:49], v[164:167], v[180:183], v[46:49]
	v_mfma_f32_16x16x32_bf16 v[38:41], v[156:159], v[188:191], v[38:41]
	v_mfma_f32_16x16x32_bf16 v[30:33], v[164:167], v[188:191], v[30:33]
	v_mfma_f32_16x16x32_bf16 v[22:25], v[156:159], v[196:199], v[22:25]
	v_mfma_f32_16x16x32_bf16 v[14:17], v[164:167], v[196:199], v[14:17]
	v_mfma_f32_16x16x32_bf16 v[50:53], v[200:203], v[168:171], v[50:53]
	v_mfma_f32_16x16x32_bf16 v[42:45], v[208:211], v[168:171], v[42:45]
	v_mfma_f32_16x16x32_bf16 v[34:37], v[200:203], v[176:179], v[34:37]
	v_mfma_f32_16x16x32_bf16 v[26:29], v[208:211], v[176:179], v[26:29]
	v_mfma_f32_16x16x32_bf16 v[18:21], v[200:203], v[184:187], v[18:21]
	v_mfma_f32_16x16x32_bf16 v[10:13], v[208:211], v[184:187], v[10:13]
	v_mfma_f32_16x16x32_bf16 v[6:9], v[200:203], v[192:195], v[6:9]
	v_mfma_f32_16x16x32_bf16 v[2:5], v[208:211], v[192:195], v[2:5]
	v_mfma_f32_16x16x32_bf16 v[50:53], v[204:207], v[172:175], v[50:53]
	v_mfma_f32_16x16x32_bf16 v[42:45], v[212:215], v[172:175], v[42:45]
	v_mfma_f32_16x16x32_bf16 v[34:37], v[204:207], v[180:183], v[34:37]
	v_mfma_f32_16x16x32_bf16 v[26:29], v[212:215], v[180:183], v[26:29]
	v_mfma_f32_16x16x32_bf16 v[18:21], v[204:207], v[188:191], v[18:21]
	v_mfma_f32_16x16x32_bf16 v[10:13], v[212:215], v[188:191], v[10:13]
	v_mfma_f32_16x16x32_bf16 v[6:9], v[204:207], v[196:199], v[6:9]
	v_mfma_f32_16x16x32_bf16 v[2:5], v[212:215], v[196:199], v[2:5]
	s_setprio 0
	s_add_i32 s60, s60, 2
	s_add_u32 s21, s21, 0x100
	s_addc_u32 s23, s23, 0
	s_add_u32 s38, s38, 0x100
	s_addc_u32 s39, s39, 0
	s_cmp_gt_u32 s60, 61
	s_barrier
	s_cbranch_scc0 .LBB0_4133
	v_lshl_add_u32 v152, s36, 8, v1
	v_lshl_or_b32 v144, s59, 8, v147
	v_ashrrev_i32_e32 v153, 31, v152
	v_ashrrev_i32_e32 v145, 31, v144
	v_lshlrev_b64 v[154:155], 13, v[152:153]
	v_lshl_add_u64 v[154:155], s[8:9], 0, v[154:155]
	v_lshlrev_b64 v[156:157], 1, v[144:145]
	v_lshl_add_u64 v[144:145], v[154:155], 0, v[156:157]
	v_cvt_pk_bf16_f32 v126, v126, v127
	v_cvt_pk_bf16_f32 v127, v128, v129
	v_cvt_pk_bf16_f32 v128, v122, v123
	v_cvt_pk_bf16_f32 v129, v124, v125
	global_store_dwordx4 v[144:145], v[126:129], off
	v_cvt_pk_bf16_f32 v118, v118, v119
	v_cvt_pk_bf16_f32 v119, v120, v121
	v_cvt_pk_bf16_f32 v120, v110, v111
	v_or_b32_e32 v110, 16, v152
	v_ashrrev_i32_e32 v111, 31, v110
	v_lshlrev_b64 v[110:111], 13, v[110:111]
	v_lshl_add_u64 v[110:111], s[8:9], 0, v[110:111]
	v_cvt_pk_bf16_f32 v121, v112, v113
	global_store_dwordx4 v[144:145], v[118:121], off offset:256
	s_mov_b32 s36, s22
	s_mov_b32 s59, s20
	v_lshl_add_u64 v[118:119], v[110:111], 0, v[156:157]
	v_cvt_pk_bf16_f32 v110, v114, v115
	v_cvt_pk_bf16_f32 v111, v116, v117
	v_cvt_pk_bf16_f32 v112, v106, v107
	v_cvt_pk_bf16_f32 v113, v108, v109
	global_store_dwordx4 v[118:119], v[110:113], off
	v_cvt_pk_bf16_f32 v102, v102, v103
	v_cvt_pk_bf16_f32 v103, v104, v105
	v_cvt_pk_bf16_f32 v104, v94, v95
	v_or_b32_e32 v94, 32, v152
	v_ashrrev_i32_e32 v95, 31, v94
	v_lshlrev_b64 v[94:95], 13, v[94:95]
	v_lshl_add_u64 v[94:95], s[8:9], 0, v[94:95]
	v_cvt_pk_bf16_f32 v105, v96, v97
	global_store_dwordx4 v[118:119], v[102:105], off offset:256
	s_mov_b64 s[40:41], s[34:35]
	s_mov_b64 s[38:39], s[26:27]
	v_lshl_add_u64 v[102:103], v[94:95], 0, v[156:157]
	v_cvt_pk_bf16_f32 v94, v98, v99
	v_cvt_pk_bf16_f32 v95, v100, v101
	v_cvt_pk_bf16_f32 v96, v90, v91
	v_cvt_pk_bf16_f32 v97, v92, v93
	global_store_dwordx4 v[102:103], v[94:97], off
	v_cvt_pk_bf16_f32 v86, v86, v87
	v_cvt_pk_bf16_f32 v87, v88, v89
	v_cvt_pk_bf16_f32 v88, v78, v79
	v_or_b32_e32 v78, 48, v152
	v_ashrrev_i32_e32 v79, 31, v78
	v_lshlrev_b64 v[78:79], 13, v[78:79]
	v_lshl_add_u64 v[78:79], s[8:9], 0, v[78:79]
	v_cvt_pk_bf16_f32 v89, v80, v81
	global_store_dwordx4 v[102:103], v[86:89], off offset:256
	s_nop 1
	v_lshl_add_u64 v[86:87], v[78:79], 0, v[156:157]
	v_cvt_pk_bf16_f32 v78, v82, v83
	v_cvt_pk_bf16_f32 v79, v84, v85
	v_cvt_pk_bf16_f32 v80, v74, v75
	v_cvt_pk_bf16_f32 v81, v76, v77
	global_store_dwordx4 v[86:87], v[78:81], off
	v_cvt_pk_bf16_f32 v70, v70, v71
	v_cvt_pk_bf16_f32 v71, v72, v73
	v_cvt_pk_bf16_f32 v72, v66, v67
	v_cvt_pk_bf16_f32 v73, v68, v69
	global_store_dwordx4 v[86:87], v[70:73], off offset:256
	v_cvt_pk_bf16_f32 v62, v62, v63
	v_cvt_pk_bf16_f32 v63, v64, v65
	v_cvt_pk_bf16_f32 v64, v58, v59
	v_add_co_u32_e32 v58, vcc, s55, v144
	v_lshl_add_u64 v[66:67], v[144:145], 0, s[6:7]
	s_nop 0
	v_addc_co_u32_e32 v59, vcc, 0, v145, vcc
	v_cvt_pk_bf16_f32 v65, v60, v61
	global_store_dwordx4 v[58:59], v[62:65], off
	v_cvt_pk_bf16_f32 v50, v50, v51
	v_cvt_pk_bf16_f32 v51, v52, v53
	v_cvt_pk_bf16_f32 v52, v42, v43
	v_cvt_pk_bf16_f32 v53, v44, v45
	global_store_dwordx4 v[66:67], v[50:53], off offset:256
	v_cvt_pk_bf16_f32 v42, v54, v55
	v_cvt_pk_bf16_f32 v43, v56, v57
	v_cvt_pk_bf16_f32 v44, v46, v47
	v_add_co_u32_e32 v46, vcc, s56, v144
	s_nop 0
	v_lshl_add_u64 v[50:51], v[144:145], 0, s[14:15]
	v_addc_co_u32_e32 v47, vcc, 0, v145, vcc
	v_cvt_pk_bf16_f32 v45, v48, v49
	global_store_dwordx4 v[46:47], v[42:45], off
	v_cvt_pk_bf16_f32 v34, v34, v35
	v_cvt_pk_bf16_f32 v35, v36, v37
	v_cvt_pk_bf16_f32 v36, v26, v27
	v_cvt_pk_bf16_f32 v37, v28, v29
	global_store_dwordx4 v[50:51], v[34:37], off offset:256
	v_cvt_pk_bf16_f32 v26, v38, v39
	v_cvt_pk_bf16_f32 v27, v40, v41
	v_cvt_pk_bf16_f32 v28, v30, v31
	v_add_co_u32_e32 v30, vcc, s57, v144
	s_nop 0
	v_lshl_add_u64 v[34:35], v[144:145], 0, s[16:17]
	v_addc_co_u32_e32 v31, vcc, 0, v145, vcc
	v_cvt_pk_bf16_f32 v29, v32, v33
	global_store_dwordx4 v[30:31], v[26:29], off
	v_cvt_pk_bf16_f32 v18, v18, v19
	v_cvt_pk_bf16_f32 v19, v20, v21
	v_cvt_pk_bf16_f32 v20, v10, v11
	v_cvt_pk_bf16_f32 v21, v12, v13
	global_store_dwordx4 v[34:35], v[18:21], off offset:256
	v_cvt_pk_bf16_f32 v10, v22, v23
	v_cvt_pk_bf16_f32 v11, v24, v25
	v_cvt_pk_bf16_f32 v12, v14, v15
	v_add_co_u32_e32 v14, vcc, s58, v144
	s_nop 0
	v_lshl_add_u64 v[18:19], v[144:145], 0, s[18:19]
	v_addc_co_u32_e32 v15, vcc, 0, v145, vcc
	s_and_b64 vcc, exec, s[4:5]
	v_cvt_pk_bf16_f32 v13, v16, v17
	global_store_dwordx4 v[14:15], v[10:13], off
	v_cvt_pk_bf16_f32 v6, v6, v7
	v_cvt_pk_bf16_f32 v7, v8, v9
	v_cvt_pk_bf16_f32 v8, v2, v3
	v_cvt_pk_bf16_f32 v9, v4, v5
	global_store_dwordx4 v[18:19], v[6:9], off offset:256
	s_cbranch_vccz .LBB0_4126
	s_waitcnt vmcnt(0)
	s_cmpk_gt_u32 s11, 0xff
	s_cbranch_scc1 .LBB0_4137
	s_barrier
